# P0 weight transposes: all 32 row-piece loads of a 64x32 item in flight at once instead of 4 serialized batches of 8
# speedup vs baseline: 1.0054x; 1.0012x over previous
; #define LAS __attribute__((address_space(3)))
; __device__ __forceinline__ unsigned pk2(float lo, float hi) { unsigned r; asm("v_cvt_pk_bf16_f32 %0, %1, %2" : "=v"(r) : "v"(lo), "v"(hi)); return r; }
; __device__ __forceinline__ int rowmap_ffn(int n) { if (n < DFF) return 256 * (n >> 7) + (n & 127); const int j = n - DFF; return 256 * (j >> 7) + 128 + (j & 127); }
; __device__ __forceinline__ void transpose_item(const float* W, int K, int N, bf16_t* WT, int mapk, LAS float* scr, int item, int lane) {
;     const int nblk = N / 32, kb = item / nblk, nb = item % nblk, k0 = 64 * kb, n0 = 32 * nb;
; #pragma unroll 8
;     for (int i = 0; i < 32; ++i) { const int kk = 2 * i + (lane >> 5); scr[kk * 33 + (lane & 31)] = __builtin_nontemporal_load(&W[(size_t)(k0 + kk) * N + n0 + (lane & 31)]); }
;     asm volatile("s_waitcnt lgkmcnt(0)" ::: "memory");
;     const int c = lane & 7;
; #pragma unroll
;     for (int j = 0; j < 4; ++j) { const int n = (lane >> 3) + 8 * j; const LAS float* s = scr + (8 * c) * 33 + n;
;         u32x4 o; o.x = pk2(s[0 * 33], s[1 * 33]); o.y = pk2(s[2 * 33], s[3 * 33]); o.z = pk2(s[4 * 33], s[5 * 33]); o.w = pk2(s[6 * 33], s[7 * 33]);
;         const int nn = n0 + n; const int row = mapk == 0 ? nn : (mapk == 1 ? rowmap_ffn(nn) : rowmap_win(nn));
;         *(u32x4*)(WT + (size_t)row * K + k0 + 8 * c) = o; }
;     asm volatile("s_waitcnt lgkmcnt(0)" ::: "memory");
; }
.LBB0_17:
	v_lshl_add_u64 v[54:55], v[38:39], 0, s[6:7]
	v_lshl_add_u64 v[56:57], v[36:37], 0, s[6:7]
	v_lshl_add_u64 v[58:59], v[34:35], 0, s[6:7]
	v_lshl_add_u64 v[60:61], v[32:33], 0, s[6:7]
	v_lshl_add_u64 v[62:63], v[30:31], 0, s[6:7]
	v_lshl_add_u64 v[64:65], v[28:29], 0, s[6:7]
	v_lshl_add_u64 v[66:67], v[4:5], 0, s[6:7]
	v_lshl_add_u64 v[68:69], v[2:3], 0, s[6:7]
	global_load_dword v80, v[54:55], off nt
	global_load_dword v81, v[56:57], off nt
	global_load_dword v82, v[58:59], off nt
	global_load_dword v83, v[60:61], off nt
	global_load_dword v84, v[62:63], off nt
	global_load_dword v85, v[64:65], off nt
	global_load_dword v86, v[66:67], off nt
	global_load_dword v87, v[68:69], off nt
	s_add_u32 s6, s6, 0x10000
	s_addc_u32 s7, s7, 0
	v_lshl_add_u64 v[54:55], v[38:39], 0, s[6:7]
	v_lshl_add_u64 v[56:57], v[36:37], 0, s[6:7]
	v_lshl_add_u64 v[58:59], v[34:35], 0, s[6:7]
	v_lshl_add_u64 v[60:61], v[32:33], 0, s[6:7]
	v_lshl_add_u64 v[62:63], v[30:31], 0, s[6:7]
	v_lshl_add_u64 v[64:65], v[28:29], 0, s[6:7]
	v_lshl_add_u64 v[66:67], v[4:5], 0, s[6:7]
	v_lshl_add_u64 v[68:69], v[2:3], 0, s[6:7]
	global_load_dword v88, v[54:55], off nt
	global_load_dword v89, v[56:57], off nt
	global_load_dword v90, v[58:59], off nt
	global_load_dword v91, v[60:61], off nt
	global_load_dword v92, v[62:63], off nt
	global_load_dword v93, v[64:65], off nt
	global_load_dword v94, v[66:67], off nt
	global_load_dword v95, v[68:69], off nt
	s_add_u32 s6, s6, 0x10000
	s_addc_u32 s7, s7, 0
	v_lshl_add_u64 v[54:55], v[38:39], 0, s[6:7]
	v_lshl_add_u64 v[56:57], v[36:37], 0, s[6:7]
	v_lshl_add_u64 v[58:59], v[34:35], 0, s[6:7]
	v_lshl_add_u64 v[60:61], v[32:33], 0, s[6:7]
	v_lshl_add_u64 v[62:63], v[30:31], 0, s[6:7]
	v_lshl_add_u64 v[64:65], v[28:29], 0, s[6:7]
	v_lshl_add_u64 v[66:67], v[4:5], 0, s[6:7]
	v_lshl_add_u64 v[68:69], v[2:3], 0, s[6:7]
	global_load_dword v96, v[54:55], off nt
	global_load_dword v97, v[56:57], off nt
	global_load_dword v98, v[58:59], off nt
	global_load_dword v99, v[60:61], off nt
	global_load_dword v100, v[62:63], off nt
	global_load_dword v101, v[64:65], off nt
	global_load_dword v102, v[66:67], off nt
	global_load_dword v103, v[68:69], off nt
	s_add_u32 s6, s6, 0x10000
	s_addc_u32 s7, s7, 0
	v_lshl_add_u64 v[54:55], v[38:39], 0, s[6:7]
	v_lshl_add_u64 v[56:57], v[36:37], 0, s[6:7]
	v_lshl_add_u64 v[58:59], v[34:35], 0, s[6:7]
	v_lshl_add_u64 v[60:61], v[32:33], 0, s[6:7]
	v_lshl_add_u64 v[62:63], v[30:31], 0, s[6:7]
	v_lshl_add_u64 v[64:65], v[28:29], 0, s[6:7]
	v_lshl_add_u64 v[66:67], v[4:5], 0, s[6:7]
	v_lshl_add_u64 v[68:69], v[2:3], 0, s[6:7]
	global_load_dword v104, v[54:55], off nt
	global_load_dword v105, v[56:57], off nt
	global_load_dword v106, v[58:59], off nt
	global_load_dword v107, v[60:61], off nt
	global_load_dword v108, v[62:63], off nt
	global_load_dword v109, v[64:65], off nt
	global_load_dword v110, v[66:67], off nt
	global_load_dword v111, v[68:69], off nt
	s_add_u32 s6, s6, 0x10000
	s_addc_u32 s7, s7, 0
	v_add_u32_e32 v62, 0x400, v8
	s_waitcnt vmcnt(30)
	ds_write2_b32 v8, v80, v81 offset1:66
	s_waitcnt vmcnt(28)
	ds_write2_b32 v8, v82, v83 offset0:132 offset1:198
	s_waitcnt vmcnt(26)
	ds_write2_b32 v62, v84, v85 offset0:8 offset1:74
	s_waitcnt vmcnt(24)
	ds_write2_b32 v62, v86, v87 offset0:140 offset1:206
	v_add_u32_e32 v8, 0x840, v8
	v_add_u32_e32 v62, 0x400, v8
	s_waitcnt vmcnt(22)
	ds_write2_b32 v8, v88, v89 offset1:66
	s_waitcnt vmcnt(20)
	ds_write2_b32 v8, v90, v91 offset0:132 offset1:198
	s_waitcnt vmcnt(18)
	ds_write2_b32 v62, v92, v93 offset0:8 offset1:74
	s_waitcnt vmcnt(16)
	ds_write2_b32 v62, v94, v95 offset0:140 offset1:206
	v_add_u32_e32 v8, 0x840, v8
	v_add_u32_e32 v62, 0x400, v8
	s_waitcnt vmcnt(14)
	ds_write2_b32 v8, v96, v97 offset1:66
	s_waitcnt vmcnt(12)
	ds_write2_b32 v8, v98, v99 offset0:132 offset1:198
	s_waitcnt vmcnt(10)
	ds_write2_b32 v62, v100, v101 offset0:8 offset1:74
	s_waitcnt vmcnt(8)
	ds_write2_b32 v62, v102, v103 offset0:140 offset1:206
	v_add_u32_e32 v8, 0x840, v8
	v_add_u32_e32 v62, 0x400, v8
	s_waitcnt vmcnt(6)
	ds_write2_b32 v8, v104, v105 offset1:66
	s_waitcnt vmcnt(4)
	ds_write2_b32 v8, v106, v107 offset0:132 offset1:198
	s_waitcnt vmcnt(2)
	ds_write2_b32 v62, v108, v109 offset0:8 offset1:74
	s_waitcnt vmcnt(0)
	ds_write2_b32 v62, v110, v111 offset0:140 offset1:206
	v_add_u32_e32 v8, 0x840, v8
	s_cmp_lg_u32 s6, 0x40000
	s_waitcnt lgkmcnt(0)
	s_add_i32 s6, s31, 0x18a00
	ds_read2_b32 v[28:29], v41 offset0:33 offset1:41
	ds_read2_b32 v[30:31], v41 offset1:8
	ds_read2_b32 v[32:33], v41 offset0:66 offset1:74
	ds_read2_b32 v[34:35], v41 offset0:99 offset1:107
	ds_read2_b32 v[36:37], v41 offset0:132 offset1:140
	ds_read2_b32 v[38:39], v41 offset0:165 offset1:173
	ds_read2_b32 v[54:55], v41 offset0:198 offset1:206
	ds_read2_b32 v[56:57], v41 offset0:231 offset1:239
	s_and_b32 s6, s6, 0x1ffc0
	s_lshl_b32 s24, s6, 1
	v_or_b32_e32 v8, s30, v40
	v_lshl_add_u64 v[58:59], v[12:13], 0, s[24:25]
	v_lshlrev_b32_e32 v8, 11, v8
	v_lshl_add_u64 v[60:61], v[58:59], 0, v[8:9]
	s_waitcnt lgkmcnt(6)
	v_cvt_pk_bf16_f32 v2, v30, v28
	s_waitcnt lgkmcnt(4)
	v_cvt_pk_bf16_f32 v3, v32, v34
	s_waitcnt lgkmcnt(2)
	v_cvt_pk_bf16_f32 v4, v36, v38
	s_waitcnt lgkmcnt(0)
	v_cvt_pk_bf16_f32 v5, v54, v56
	global_store_dwordx4 v[60:61], v[2:5], off
	v_or_b32_e32 v8, s30, v42
	v_lshlrev_b32_e32 v8, 11, v8
	v_cvt_pk_bf16_f32 v2, v31, v29
	v_cvt_pk_bf16_f32 v3, v33, v35
	v_cvt_pk_bf16_f32 v4, v37, v39
	v_cvt_pk_bf16_f32 v5, v55, v57
	ds_read2_b32 v[30:31], v41 offset0:16 offset1:24
	ds_read2_b32 v[32:33], v41 offset0:49 offset1:57
	ds_read2_b32 v[34:35], v41 offset0:82 offset1:90
	ds_read2_b32 v[36:37], v41 offset0:115 offset1:123
	ds_read2_b32 v[38:39], v41 offset0:148 offset1:156
	ds_read2_b32 v[54:55], v41 offset0:181 offset1:189
	ds_read2_b32 v[56:57], v41 offset0:214 offset1:222
	ds_read2_b32 v[60:61], v41 offset0:247 offset1:255
	v_lshl_add_u64 v[28:29], v[58:59], 0, v[8:9]
	v_or_b32_e32 v8, s30, v43
	v_lshlrev_b32_e32 v8, 11, v8
	global_store_dwordx4 v[28:29], v[2:5], off
	v_lshl_add_u64 v[28:29], v[58:59], 0, v[8:9]
	v_or_b32_e32 v8, s30, v44
	v_lshlrev_b32_e32 v8, 11, v8
	s_waitcnt lgkmcnt(6)
	v_cvt_pk_bf16_f32 v2, v30, v32
	s_waitcnt lgkmcnt(4)
	v_cvt_pk_bf16_f32 v3, v34, v36
	s_waitcnt lgkmcnt(2)
	v_cvt_pk_bf16_f32 v4, v38, v54
	s_waitcnt lgkmcnt(0)
	v_cvt_pk_bf16_f32 v5, v56, v60
	global_store_dwordx4 v[28:29], v[2:5], off
	v_lshl_add_u64 v[28:29], v[58:59], 0, v[8:9]
	s_mov_b64 s[6:7], 0
	v_cvt_pk_bf16_f32 v2, v31, v33
	v_cvt_pk_bf16_f32 v3, v35, v37
	v_cvt_pk_bf16_f32 v4, v39, v55
	v_cvt_pk_bf16_f32 v5, v57, v61
	global_store_dwordx4 v[28:29], v[2:5], off
	s_waitcnt lgkmcnt(0)

; #define LAS __attribute__((address_space(3)))
; __device__ __forceinline__ unsigned pk2(float lo, float hi) { unsigned r; asm("v_cvt_pk_bf16_f32 %0, %1, %2" : "=v"(r) : "v"(lo), "v"(hi)); return r; }
; __device__ __forceinline__ int rowmap_ffn(int n) { if (n < DFF) return 256 * (n >> 7) + (n & 127); const int j = n - DFF; return 256 * (j >> 7) + 128 + (j & 127); }
; __device__ __forceinline__ void transpose_item(const float* W, int K, int N, bf16_t* WT, int mapk, LAS float* scr, int item, int lane) {
;     const int nblk = N / 32, kb = item / nblk, nb = item % nblk, k0 = 64 * kb, n0 = 32 * nb;
; #pragma unroll 8
;     for (int i = 0; i < 32; ++i) { const int kk = 2 * i + (lane >> 5); scr[kk * 33 + (lane & 31)] = __builtin_nontemporal_load(&W[(size_t)(k0 + kk) * N + n0 + (lane & 31)]); }
;     asm volatile("s_waitcnt lgkmcnt(0)" ::: "memory");
;     const int c = lane & 7;
; #pragma unroll
;     for (int j = 0; j < 4; ++j) { const int n = (lane >> 3) + 8 * j; const LAS float* s = scr + (8 * c) * 33 + n;
;         u32x4 o; o.x = pk2(s[0 * 33], s[1 * 33]); o.y = pk2(s[2 * 33], s[3 * 33]); o.z = pk2(s[4 * 33], s[5 * 33]); o.w = pk2(s[6 * 33], s[7 * 33]);
;         const int nn = n0 + n; const int row = mapk == 0 ? nn : (mapk == 1 ? rowmap_ffn(nn) : rowmap_win(nn));
;         *(u32x4*)(WT + (size_t)row * K + k0 + 8 * c) = o; }
;     asm volatile("s_waitcnt lgkmcnt(0)" ::: "memory");
; }
.LBB0_21:
	v_lshl_add_u64 v[54:55], v[38:39], 0, s[6:7]
	v_lshl_add_u64 v[56:57], v[36:37], 0, s[6:7]
	v_lshl_add_u64 v[58:59], v[34:35], 0, s[6:7]
	v_lshl_add_u64 v[60:61], v[32:33], 0, s[6:7]
	v_lshl_add_u64 v[62:63], v[30:31], 0, s[6:7]
	v_lshl_add_u64 v[64:65], v[28:29], 0, s[6:7]
	v_lshl_add_u64 v[66:67], v[4:5], 0, s[6:7]
	v_lshl_add_u64 v[68:69], v[2:3], 0, s[6:7]
	global_load_dword v80, v[54:55], off nt
	global_load_dword v81, v[56:57], off nt
	global_load_dword v82, v[58:59], off nt
	global_load_dword v83, v[60:61], off nt
	global_load_dword v84, v[62:63], off nt
	global_load_dword v85, v[64:65], off nt
	global_load_dword v86, v[66:67], off nt
	global_load_dword v87, v[68:69], off nt
	s_add_u32 s6, s6, 0x10000
	s_addc_u32 s7, s7, 0
	v_lshl_add_u64 v[54:55], v[38:39], 0, s[6:7]
	v_lshl_add_u64 v[56:57], v[36:37], 0, s[6:7]
	v_lshl_add_u64 v[58:59], v[34:35], 0, s[6:7]
	v_lshl_add_u64 v[60:61], v[32:33], 0, s[6:7]
	v_lshl_add_u64 v[62:63], v[30:31], 0, s[6:7]
	v_lshl_add_u64 v[64:65], v[28:29], 0, s[6:7]
	v_lshl_add_u64 v[66:67], v[4:5], 0, s[6:7]
	v_lshl_add_u64 v[68:69], v[2:3], 0, s[6:7]
	global_load_dword v88, v[54:55], off nt
	global_load_dword v89, v[56:57], off nt
	global_load_dword v90, v[58:59], off nt
	global_load_dword v91, v[60:61], off nt
	global_load_dword v92, v[62:63], off nt
	global_load_dword v93, v[64:65], off nt
	global_load_dword v94, v[66:67], off nt
	global_load_dword v95, v[68:69], off nt
	s_add_u32 s6, s6, 0x10000
	s_addc_u32 s7, s7, 0
	v_lshl_add_u64 v[54:55], v[38:39], 0, s[6:7]
	v_lshl_add_u64 v[56:57], v[36:37], 0, s[6:7]
	v_lshl_add_u64 v[58:59], v[34:35], 0, s[6:7]
	v_lshl_add_u64 v[60:61], v[32:33], 0, s[6:7]
	v_lshl_add_u64 v[62:63], v[30:31], 0, s[6:7]
	v_lshl_add_u64 v[64:65], v[28:29], 0, s[6:7]
	v_lshl_add_u64 v[66:67], v[4:5], 0, s[6:7]
	v_lshl_add_u64 v[68:69], v[2:3], 0, s[6:7]
	global_load_dword v96, v[54:55], off nt
	global_load_dword v97, v[56:57], off nt
	global_load_dword v98, v[58:59], off nt
	global_load_dword v99, v[60:61], off nt
	global_load_dword v100, v[62:63], off nt
	global_load_dword v101, v[64:65], off nt
	global_load_dword v102, v[66:67], off nt
	global_load_dword v103, v[68:69], off nt
	s_add_u32 s6, s6, 0x10000
	s_addc_u32 s7, s7, 0
	v_lshl_add_u64 v[54:55], v[38:39], 0, s[6:7]
	v_lshl_add_u64 v[56:57], v[36:37], 0, s[6:7]
	v_lshl_add_u64 v[58:59], v[34:35], 0, s[6:7]
	v_lshl_add_u64 v[60:61], v[32:33], 0, s[6:7]
	v_lshl_add_u64 v[62:63], v[30:31], 0, s[6:7]
	v_lshl_add_u64 v[64:65], v[28:29], 0, s[6:7]
	v_lshl_add_u64 v[66:67], v[4:5], 0, s[6:7]
	v_lshl_add_u64 v[68:69], v[2:3], 0, s[6:7]
	global_load_dword v104, v[54:55], off nt
	global_load_dword v105, v[56:57], off nt
	global_load_dword v106, v[58:59], off nt
	global_load_dword v107, v[60:61], off nt
	global_load_dword v108, v[62:63], off nt
	global_load_dword v109, v[64:65], off nt
	global_load_dword v110, v[66:67], off nt
	global_load_dword v111, v[68:69], off nt
	s_add_u32 s6, s6, 0x10000
	s_addc_u32 s7, s7, 0
	v_add_u32_e32 v62, 0x400, v8
	s_waitcnt vmcnt(30)
	ds_write2_b32 v8, v80, v81 offset1:66
	s_waitcnt vmcnt(28)
	ds_write2_b32 v8, v82, v83 offset0:132 offset1:198
	s_waitcnt vmcnt(26)
	ds_write2_b32 v62, v84, v85 offset0:8 offset1:74
	s_waitcnt vmcnt(24)
	ds_write2_b32 v62, v86, v87 offset0:140 offset1:206
	v_add_u32_e32 v8, 0x840, v8
	v_add_u32_e32 v62, 0x400, v8
	s_waitcnt vmcnt(22)
	ds_write2_b32 v8, v88, v89 offset1:66
	s_waitcnt vmcnt(20)
	ds_write2_b32 v8, v90, v91 offset0:132 offset1:198
	s_waitcnt vmcnt(18)
	ds_write2_b32 v62, v92, v93 offset0:8 offset1:74
	s_waitcnt vmcnt(16)
	ds_write2_b32 v62, v94, v95 offset0:140 offset1:206
	v_add_u32_e32 v8, 0x840, v8
	v_add_u32_e32 v62, 0x400, v8
	s_waitcnt vmcnt(14)
	ds_write2_b32 v8, v96, v97 offset1:66
	s_waitcnt vmcnt(12)
	ds_write2_b32 v8, v98, v99 offset0:132 offset1:198
	s_waitcnt vmcnt(10)
	ds_write2_b32 v62, v100, v101 offset0:8 offset1:74
	s_waitcnt vmcnt(8)
	ds_write2_b32 v62, v102, v103 offset0:140 offset1:206
	v_add_u32_e32 v8, 0x840, v8
	v_add_u32_e32 v62, 0x400, v8
	s_waitcnt vmcnt(6)
	ds_write2_b32 v8, v104, v105 offset1:66
	s_waitcnt vmcnt(4)
	ds_write2_b32 v8, v106, v107 offset0:132 offset1:198
	s_waitcnt vmcnt(2)
	ds_write2_b32 v62, v108, v109 offset0:8 offset1:74
	s_waitcnt vmcnt(0)
	ds_write2_b32 v62, v110, v111 offset0:140 offset1:206
	v_add_u32_e32 v8, 0x840, v8
	s_cmp_lg_u32 s6, 0x40000
	s_waitcnt lgkmcnt(0)
	s_add_i32 s31, s31, 0x18e00
	ds_read2_b32 v[28:29], v41 offset0:33 offset1:41
	ds_read2_b32 v[30:31], v41 offset1:8
	ds_read2_b32 v[32:33], v41 offset0:66 offset1:74
	ds_read2_b32 v[34:35], v41 offset0:99 offset1:107
	ds_read2_b32 v[36:37], v41 offset0:132 offset1:140
	ds_read2_b32 v[38:39], v41 offset0:165 offset1:173
	ds_read2_b32 v[54:55], v41 offset0:198 offset1:206
	ds_read2_b32 v[56:57], v41 offset0:231 offset1:239
	s_and_b32 s6, s31, 0x1ffc0
	s_lshl_b32 s24, s6, 1
	v_or_b32_e32 v8, s30, v40
	v_lshl_add_u64 v[58:59], v[14:15], 0, s[24:25]
	v_lshlrev_b32_e32 v8, 11, v8
	v_lshl_add_u64 v[60:61], v[58:59], 0, v[8:9]
	s_waitcnt lgkmcnt(6)
	v_cvt_pk_bf16_f32 v2, v30, v28
	s_waitcnt lgkmcnt(4)
	v_cvt_pk_bf16_f32 v3, v32, v34
	s_waitcnt lgkmcnt(2)
	v_cvt_pk_bf16_f32 v4, v36, v38
	s_waitcnt lgkmcnt(0)
	v_cvt_pk_bf16_f32 v5, v54, v56
	global_store_dwordx4 v[60:61], v[2:5], off
	v_or_b32_e32 v8, s30, v42
	v_lshlrev_b32_e32 v8, 11, v8
	v_cvt_pk_bf16_f32 v2, v31, v29
	v_cvt_pk_bf16_f32 v3, v33, v35
	v_cvt_pk_bf16_f32 v4, v37, v39
	v_cvt_pk_bf16_f32 v5, v55, v57
	ds_read2_b32 v[30:31], v41 offset0:16 offset1:24
	ds_read2_b32 v[32:33], v41 offset0:49 offset1:57
	ds_read2_b32 v[34:35], v41 offset0:82 offset1:90
	ds_read2_b32 v[36:37], v41 offset0:115 offset1:123
	ds_read2_b32 v[38:39], v41 offset0:148 offset1:156
	ds_read2_b32 v[54:55], v41 offset0:181 offset1:189
	ds_read2_b32 v[56:57], v41 offset0:214 offset1:222
	ds_read2_b32 v[60:61], v41 offset0:247 offset1:255
	v_lshl_add_u64 v[28:29], v[58:59], 0, v[8:9]
	v_or_b32_e32 v8, s30, v43
	v_lshlrev_b32_e32 v8, 11, v8
	global_store_dwordx4 v[28:29], v[2:5], off
	v_lshl_add_u64 v[28:29], v[58:59], 0, v[8:9]
	v_or_b32_e32 v8, s30, v44
	v_lshlrev_b32_e32 v8, 11, v8
	s_waitcnt lgkmcnt(6)
	v_cvt_pk_bf16_f32 v2, v30, v32
	s_waitcnt lgkmcnt(4)
	v_cvt_pk_bf16_f32 v3, v34, v36
	s_waitcnt lgkmcnt(2)
	v_cvt_pk_bf16_f32 v4, v38, v54
	s_waitcnt lgkmcnt(0)
	v_cvt_pk_bf16_f32 v5, v56, v60
	global_store_dwordx4 v[28:29], v[2:5], off
	v_lshl_add_u64 v[28:29], v[58:59], 0, v[8:9]
	s_nop 0
	v_cvt_pk_bf16_f32 v2, v31, v33
	v_cvt_pk_bf16_f32 v3, v35, v37
	v_cvt_pk_bf16_f32 v4, v39, v55
	v_cvt_pk_bf16_f32 v5, v57, v61
	global_store_dwordx4 v[28:29], v[2:5], off
	s_waitcnt lgkmcnt(0)

; #define LAS __attribute__((address_space(3)))
; __device__ __forceinline__ unsigned pk2(float lo, float hi) { unsigned r; asm("v_cvt_pk_bf16_f32 %0, %1, %2" : "=v"(r) : "v"(lo), "v"(hi)); return r; }
; __device__ __forceinline__ int rowmap_ffn(int n) { if (n < DFF) return 256 * (n >> 7) + (n & 127); const int j = n - DFF; return 256 * (j >> 7) + 128 + (j & 127); }
; __device__ __forceinline__ void transpose_item(const float* W, int K, int N, bf16_t* WT, int mapk, LAS float* scr, int item, int lane) {
;     const int nblk = N / 32, kb = item / nblk, nb = item % nblk, k0 = 64 * kb, n0 = 32 * nb;
; #pragma unroll 8
;     for (int i = 0; i < 32; ++i) { const int kk = 2 * i + (lane >> 5); scr[kk * 33 + (lane & 31)] = __builtin_nontemporal_load(&W[(size_t)(k0 + kk) * N + n0 + (lane & 31)]); }
;     asm volatile("s_waitcnt lgkmcnt(0)" ::: "memory");
;     const int c = lane & 7;
; #pragma unroll
;     for (int j = 0; j < 4; ++j) { const int n = (lane >> 3) + 8 * j; const LAS float* s = scr + (8 * c) * 33 + n;
;         u32x4 o; o.x = pk2(s[0 * 33], s[1 * 33]); o.y = pk2(s[2 * 33], s[3 * 33]); o.z = pk2(s[4 * 33], s[5 * 33]); o.w = pk2(s[6 * 33], s[7 * 33]);
;         const int nn = n0 + n; const int row = mapk == 0 ? nn : (mapk == 1 ? rowmap_ffn(nn) : rowmap_win(nn));
;         *(u32x4*)(WT + (size_t)row * K + k0 + 8 * c) = o; }
;     asm volatile("s_waitcnt lgkmcnt(0)" ::: "memory");
; }
.LBB0_26:
	v_lshl_add_u64 v[54:55], v[38:39], 0, s[6:7]
	v_lshl_add_u64 v[56:57], v[36:37], 0, s[6:7]
	v_lshl_add_u64 v[58:59], v[34:35], 0, s[6:7]
	v_lshl_add_u64 v[60:61], v[32:33], 0, s[6:7]
	v_lshl_add_u64 v[62:63], v[30:31], 0, s[6:7]
	v_lshl_add_u64 v[64:65], v[28:29], 0, s[6:7]
	v_lshl_add_u64 v[66:67], v[4:5], 0, s[6:7]
	v_lshl_add_u64 v[68:69], v[2:3], 0, s[6:7]
	global_load_dword v80, v[54:55], off nt
	global_load_dword v81, v[56:57], off nt
	global_load_dword v82, v[58:59], off nt
	global_load_dword v83, v[60:61], off nt
	global_load_dword v84, v[62:63], off nt
	global_load_dword v85, v[64:65], off nt
	global_load_dword v86, v[66:67], off nt
	global_load_dword v87, v[68:69], off nt
	s_add_u32 s6, s6, 0x10000
	s_addc_u32 s7, s7, 0
	v_lshl_add_u64 v[54:55], v[38:39], 0, s[6:7]
	v_lshl_add_u64 v[56:57], v[36:37], 0, s[6:7]
	v_lshl_add_u64 v[58:59], v[34:35], 0, s[6:7]
	v_lshl_add_u64 v[60:61], v[32:33], 0, s[6:7]
	v_lshl_add_u64 v[62:63], v[30:31], 0, s[6:7]
	v_lshl_add_u64 v[64:65], v[28:29], 0, s[6:7]
	v_lshl_add_u64 v[66:67], v[4:5], 0, s[6:7]
	v_lshl_add_u64 v[68:69], v[2:3], 0, s[6:7]
	global_load_dword v88, v[54:55], off nt
	global_load_dword v89, v[56:57], off nt
	global_load_dword v90, v[58:59], off nt
	global_load_dword v91, v[60:61], off nt
	global_load_dword v92, v[62:63], off nt
	global_load_dword v93, v[64:65], off nt
	global_load_dword v94, v[66:67], off nt
	global_load_dword v95, v[68:69], off nt
	s_add_u32 s6, s6, 0x10000
	s_addc_u32 s7, s7, 0
	v_lshl_add_u64 v[54:55], v[38:39], 0, s[6:7]
	v_lshl_add_u64 v[56:57], v[36:37], 0, s[6:7]
	v_lshl_add_u64 v[58:59], v[34:35], 0, s[6:7]
	v_lshl_add_u64 v[60:61], v[32:33], 0, s[6:7]
	v_lshl_add_u64 v[62:63], v[30:31], 0, s[6:7]
	v_lshl_add_u64 v[64:65], v[28:29], 0, s[6:7]
	v_lshl_add_u64 v[66:67], v[4:5], 0, s[6:7]
	v_lshl_add_u64 v[68:69], v[2:3], 0, s[6:7]
	global_load_dword v96, v[54:55], off nt
	global_load_dword v97, v[56:57], off nt
	global_load_dword v98, v[58:59], off nt
	global_load_dword v99, v[60:61], off nt
	global_load_dword v100, v[62:63], off nt
	global_load_dword v101, v[64:65], off nt
	global_load_dword v102, v[66:67], off nt
	global_load_dword v103, v[68:69], off nt
	s_add_u32 s6, s6, 0x10000
	s_addc_u32 s7, s7, 0
	v_lshl_add_u64 v[54:55], v[38:39], 0, s[6:7]
	v_lshl_add_u64 v[56:57], v[36:37], 0, s[6:7]
	v_lshl_add_u64 v[58:59], v[34:35], 0, s[6:7]
	v_lshl_add_u64 v[60:61], v[32:33], 0, s[6:7]
	v_lshl_add_u64 v[62:63], v[30:31], 0, s[6:7]
	v_lshl_add_u64 v[64:65], v[28:29], 0, s[6:7]
	v_lshl_add_u64 v[66:67], v[4:5], 0, s[6:7]
	v_lshl_add_u64 v[68:69], v[2:3], 0, s[6:7]
	global_load_dword v104, v[54:55], off nt
	global_load_dword v105, v[56:57], off nt
	global_load_dword v106, v[58:59], off nt
	global_load_dword v107, v[60:61], off nt
	global_load_dword v108, v[62:63], off nt
	global_load_dword v109, v[64:65], off nt
	global_load_dword v110, v[66:67], off nt
	global_load_dword v111, v[68:69], off nt
	s_add_u32 s6, s6, 0x10000
	s_addc_u32 s7, s7, 0
	v_add_u32_e32 v54, 0x400, v8
	s_waitcnt vmcnt(30)
	ds_write2_b32 v8, v80, v81 offset1:66
	s_waitcnt vmcnt(28)
	ds_write2_b32 v8, v82, v83 offset0:132 offset1:198
	s_waitcnt vmcnt(26)
	ds_write2_b32 v54, v84, v85 offset0:8 offset1:74
	s_waitcnt vmcnt(24)
	ds_write2_b32 v54, v86, v87 offset0:140 offset1:206
	v_add_u32_e32 v8, 0x840, v8
	v_add_u32_e32 v54, 0x400, v8
	s_waitcnt vmcnt(22)
	ds_write2_b32 v8, v88, v89 offset1:66
	s_waitcnt vmcnt(20)
	ds_write2_b32 v8, v90, v91 offset0:132 offset1:198
	s_waitcnt vmcnt(18)
	ds_write2_b32 v54, v92, v93 offset0:8 offset1:74
	s_waitcnt vmcnt(16)
	ds_write2_b32 v54, v94, v95 offset0:140 offset1:206
	v_add_u32_e32 v8, 0x840, v8
	v_add_u32_e32 v54, 0x400, v8
	s_waitcnt vmcnt(14)
	ds_write2_b32 v8, v96, v97 offset1:66
	s_waitcnt vmcnt(12)
	ds_write2_b32 v8, v98, v99 offset0:132 offset1:198
	s_waitcnt vmcnt(10)
	ds_write2_b32 v54, v100, v101 offset0:8 offset1:74
	s_waitcnt vmcnt(8)
	ds_write2_b32 v54, v102, v103 offset0:140 offset1:206
	v_add_u32_e32 v8, 0x840, v8
	v_add_u32_e32 v54, 0x400, v8
	s_waitcnt vmcnt(6)
	ds_write2_b32 v8, v104, v105 offset1:66
	s_waitcnt vmcnt(4)
	ds_write2_b32 v8, v106, v107 offset0:132 offset1:198
	s_waitcnt vmcnt(2)
	ds_write2_b32 v54, v108, v109 offset0:8 offset1:74
	s_waitcnt vmcnt(0)
	ds_write2_b32 v54, v110, v111 offset0:140 offset1:206
	v_add_u32_e32 v8, 0x840, v8
	s_cmp_lg_u32 s6, 0x40000
	s_lshl_b32 s6, s3, 1
	s_waitcnt lgkmcnt(0)
	s_add_i32 s6, s6, 0x19600
	s_lshl_b32 s7, s3, 5
	ds_read2_b32 v[28:29], v41 offset0:33 offset1:41
	ds_read2_b32 v[30:31], v41 offset1:8
	ds_read2_b32 v[32:33], v41 offset0:66 offset1:74
	ds_read2_b32 v[34:35], v41 offset0:99 offset1:107
	ds_read2_b32 v[36:37], v41 offset0:132 offset1:140
	ds_read2_b32 v[38:39], v41 offset0:165 offset1:173
	ds_read2_b32 v[54:55], v41 offset0:198 offset1:206
	ds_read2_b32 v[56:57], v41 offset0:231 offset1:239
	s_and_b32 s6, s6, 0x1ffc0
	s_and_b32 s7, s7, 0x3e0
	s_lshl_b32 s24, s6, 1
	v_or_b32_e32 v8, s7, v40
	v_lshl_add_u64 v[58:59], v[16:17], 0, s[24:25]
	v_lshlrev_b32_e32 v8, 12, v8
	v_lshl_add_u64 v[60:61], v[58:59], 0, v[8:9]
	s_waitcnt lgkmcnt(6)
	v_cvt_pk_bf16_f32 v2, v30, v28
	s_waitcnt lgkmcnt(4)
	v_cvt_pk_bf16_f32 v3, v32, v34
	s_waitcnt lgkmcnt(2)
	v_cvt_pk_bf16_f32 v4, v36, v38
	s_waitcnt lgkmcnt(0)
	v_cvt_pk_bf16_f32 v5, v54, v56
	global_store_dwordx4 v[60:61], v[2:5], off
	v_or_b32_e32 v8, s7, v42
	v_lshlrev_b32_e32 v8, 12, v8
	v_cvt_pk_bf16_f32 v2, v31, v29
	v_cvt_pk_bf16_f32 v3, v33, v35
	v_cvt_pk_bf16_f32 v4, v37, v39
	v_cvt_pk_bf16_f32 v5, v55, v57
	ds_read2_b32 v[30:31], v41 offset0:16 offset1:24
	ds_read2_b32 v[32:33], v41 offset0:49 offset1:57
	ds_read2_b32 v[34:35], v41 offset0:82 offset1:90
	ds_read2_b32 v[36:37], v41 offset0:115 offset1:123
	ds_read2_b32 v[38:39], v41 offset0:148 offset1:156
	ds_read2_b32 v[54:55], v41 offset0:181 offset1:189
	ds_read2_b32 v[56:57], v41 offset0:214 offset1:222
	ds_read2_b32 v[60:61], v41 offset0:247 offset1:255
	v_lshl_add_u64 v[28:29], v[58:59], 0, v[8:9]
	v_or_b32_e32 v8, s7, v43
	v_lshlrev_b32_e32 v8, 12, v8
	global_store_dwordx4 v[28:29], v[2:5], off
	v_lshl_add_u64 v[28:29], v[58:59], 0, v[8:9]
	v_or_b32_e32 v8, s7, v44
	v_lshlrev_b32_e32 v8, 12, v8
	s_waitcnt lgkmcnt(6)
	v_cvt_pk_bf16_f32 v2, v30, v32
	s_waitcnt lgkmcnt(4)
	v_cvt_pk_bf16_f32 v3, v34, v36
	s_waitcnt lgkmcnt(2)
	v_cvt_pk_bf16_f32 v4, v38, v54
	s_waitcnt lgkmcnt(0)
	v_cvt_pk_bf16_f32 v5, v56, v60
	global_store_dwordx4 v[28:29], v[2:5], off
	v_lshl_add_u64 v[28:29], v[58:59], 0, v[8:9]
	s_nop 0
	v_cvt_pk_bf16_f32 v2, v31, v33
	v_cvt_pk_bf16_f32 v3, v35, v37
	v_cvt_pk_bf16_f32 v4, v39, v55
	v_cvt_pk_bf16_f32 v5, v57, v61
	global_store_dwordx4 v[28:29], v[2:5], off
	s_waitcnt lgkmcnt(0)

; #define LAS __attribute__((address_space(3)))
; __device__ __forceinline__ unsigned pk2(float lo, float hi) { unsigned r; asm("v_cvt_pk_bf16_f32 %0, %1, %2" : "=v"(r) : "v"(lo), "v"(hi)); return r; }
; __device__ __forceinline__ int rowmap_ffn(int n) { if (n < DFF) return 256 * (n >> 7) + (n & 127); const int j = n - DFF; return 256 * (j >> 7) + 128 + (j & 127); }
; __device__ __forceinline__ int rowmap_win(int n) {
;     if (n < 2048) { const int d = n & 255; const int c = d < 64 ? d : (d < 128 ? d + 64 : (d < 192 ? d - 64 : d)); return (n & ~255) + c; }
;     if (n < 6144) return n;
;     if (n < 8192) { int j = n - 6144; const int g = j >> 10; j &= 1023; return 6144 + 256 * (j >> 7) + 128 * g + (j & 127); }
;     { int j = n - 8192; const int g = j >> 10; j &= 1023; return 8192 + 256 * (j >> 7) + 128 * g + (j & 127); }
; __device__ __forceinline__ void transpose_item(const float* W, int K, int N, bf16_t* WT, int mapk, LAS float* scr, int item, int lane) {
;     ...
;     for (int i = 0; i < 32; ++i) { const int kk = 2 * i + (lane >> 5); scr[kk * 33 + (lane & 31)] = __builtin_nontemporal_load(&W[(size_t)(k0 + kk) * N + n0 + (lane & 31)]); }
;     asm volatile("s_waitcnt lgkmcnt(0)" ::: "memory");
;     const int c = lane & 7;
; #pragma unroll
;     for (int j = 0; j < 4; ++j) { const int n = (lane >> 3) + 8 * j; const LAS float* s = scr + (8 * c) * 33 + n;
;         u32x4 o; o.x = pk2(s[0 * 33], s[1 * 33]); o.y = pk2(s[2 * 33], s[3 * 33]); o.z = pk2(s[4 * 33], s[5 * 33]); o.w = pk2(s[6 * 33], s[7 * 33]);
;         const int nn = n0 + n; const int row = mapk == 0 ? nn : (mapk == 1 ? rowmap_ffn(nn) : rowmap_win(nn));
;         *(u32x4*)(WT + (size_t)row * K + k0 + 8 * c) = o; }
.LBB0_31:
	v_lshl_add_u64 v[54:55], v[38:39], 0, s[6:7]
	v_lshl_add_u64 v[56:57], v[36:37], 0, s[6:7]
	v_lshl_add_u64 v[58:59], v[34:35], 0, s[6:7]
	v_lshl_add_u64 v[60:61], v[32:33], 0, s[6:7]
	v_lshl_add_u64 v[62:63], v[30:31], 0, s[6:7]
	v_lshl_add_u64 v[64:65], v[28:29], 0, s[6:7]
	v_lshl_add_u64 v[66:67], v[4:5], 0, s[6:7]
	v_lshl_add_u64 v[68:69], v[2:3], 0, s[6:7]
	global_load_dword v80, v[54:55], off nt
	global_load_dword v81, v[56:57], off nt
	global_load_dword v82, v[58:59], off nt
	global_load_dword v83, v[60:61], off nt
	global_load_dword v84, v[62:63], off nt
	global_load_dword v85, v[64:65], off nt
	global_load_dword v86, v[66:67], off nt
	global_load_dword v87, v[68:69], off nt
	s_add_u32 s6, s6, 0xa0000
	s_addc_u32 s7, s7, 0
	v_lshl_add_u64 v[54:55], v[38:39], 0, s[6:7]
	v_lshl_add_u64 v[56:57], v[36:37], 0, s[6:7]
	v_lshl_add_u64 v[58:59], v[34:35], 0, s[6:7]
	v_lshl_add_u64 v[60:61], v[32:33], 0, s[6:7]
	v_lshl_add_u64 v[62:63], v[30:31], 0, s[6:7]
	v_lshl_add_u64 v[64:65], v[28:29], 0, s[6:7]
	v_lshl_add_u64 v[66:67], v[4:5], 0, s[6:7]
	v_lshl_add_u64 v[68:69], v[2:3], 0, s[6:7]
	global_load_dword v88, v[54:55], off nt
	global_load_dword v89, v[56:57], off nt
	global_load_dword v90, v[58:59], off nt
	global_load_dword v91, v[60:61], off nt
	global_load_dword v92, v[62:63], off nt
	global_load_dword v93, v[64:65], off nt
	global_load_dword v94, v[66:67], off nt
	global_load_dword v95, v[68:69], off nt
	s_add_u32 s6, s6, 0xa0000
	s_addc_u32 s7, s7, 0
	v_lshl_add_u64 v[54:55], v[38:39], 0, s[6:7]
	v_lshl_add_u64 v[56:57], v[36:37], 0, s[6:7]
	v_lshl_add_u64 v[58:59], v[34:35], 0, s[6:7]
	v_lshl_add_u64 v[60:61], v[32:33], 0, s[6:7]
	v_lshl_add_u64 v[62:63], v[30:31], 0, s[6:7]
	v_lshl_add_u64 v[64:65], v[28:29], 0, s[6:7]
	v_lshl_add_u64 v[66:67], v[4:5], 0, s[6:7]
	v_lshl_add_u64 v[68:69], v[2:3], 0, s[6:7]
	global_load_dword v96, v[54:55], off nt
	global_load_dword v97, v[56:57], off nt
	global_load_dword v98, v[58:59], off nt
	global_load_dword v99, v[60:61], off nt
	global_load_dword v100, v[62:63], off nt
	global_load_dword v101, v[64:65], off nt
	global_load_dword v102, v[66:67], off nt
	global_load_dword v103, v[68:69], off nt
	s_add_u32 s6, s6, 0xa0000
	s_addc_u32 s7, s7, 0
	v_lshl_add_u64 v[54:55], v[38:39], 0, s[6:7]
	v_lshl_add_u64 v[56:57], v[36:37], 0, s[6:7]
	v_lshl_add_u64 v[58:59], v[34:35], 0, s[6:7]
	v_lshl_add_u64 v[60:61], v[32:33], 0, s[6:7]
	v_lshl_add_u64 v[62:63], v[30:31], 0, s[6:7]
	v_lshl_add_u64 v[64:65], v[28:29], 0, s[6:7]
	v_lshl_add_u64 v[66:67], v[4:5], 0, s[6:7]
	v_lshl_add_u64 v[68:69], v[2:3], 0, s[6:7]
	global_load_dword v104, v[54:55], off nt
	global_load_dword v105, v[56:57], off nt
	global_load_dword v106, v[58:59], off nt
	global_load_dword v107, v[60:61], off nt
	global_load_dword v108, v[62:63], off nt
	global_load_dword v109, v[64:65], off nt
	global_load_dword v110, v[66:67], off nt
	global_load_dword v111, v[68:69], off nt
	s_add_u32 s6, s6, 0xa0000
	s_addc_u32 s7, s7, 0
	v_add_u32_e32 v62, 0x400, v8
	s_waitcnt vmcnt(30)
	ds_write2_b32 v8, v80, v81 offset1:66
	s_waitcnt vmcnt(28)
	ds_write2_b32 v8, v82, v83 offset0:132 offset1:198
	s_waitcnt vmcnt(26)
	ds_write2_b32 v62, v84, v85 offset0:8 offset1:74
	s_waitcnt vmcnt(24)
	ds_write2_b32 v62, v86, v87 offset0:140 offset1:206
	v_add_u32_e32 v8, 0x840, v8
	v_add_u32_e32 v62, 0x400, v8
	s_waitcnt vmcnt(22)
	ds_write2_b32 v8, v88, v89 offset1:66
	s_waitcnt vmcnt(20)
	ds_write2_b32 v8, v90, v91 offset0:132 offset1:198
	s_waitcnt vmcnt(18)
	ds_write2_b32 v62, v92, v93 offset0:8 offset1:74
	s_waitcnt vmcnt(16)
	ds_write2_b32 v62, v94, v95 offset0:140 offset1:206
	v_add_u32_e32 v8, 0x840, v8
	v_add_u32_e32 v62, 0x400, v8
	s_waitcnt vmcnt(14)
	ds_write2_b32 v8, v96, v97 offset1:66
	s_waitcnt vmcnt(12)
	ds_write2_b32 v8, v98, v99 offset0:132 offset1:198
	s_waitcnt vmcnt(10)
	ds_write2_b32 v62, v100, v101 offset0:8 offset1:74
	s_waitcnt vmcnt(8)
	ds_write2_b32 v62, v102, v103 offset0:140 offset1:206
	v_add_u32_e32 v8, 0x840, v8
	v_add_u32_e32 v62, 0x400, v8
	s_waitcnt vmcnt(6)
	ds_write2_b32 v8, v104, v105 offset1:66
	s_waitcnt vmcnt(4)
	ds_write2_b32 v8, v106, v107 offset0:132 offset1:198
	s_waitcnt vmcnt(2)
	ds_write2_b32 v62, v108, v109 offset0:8 offset1:74
	s_waitcnt vmcnt(0)
	ds_write2_b32 v62, v110, v111 offset0:140 offset1:206
	v_add_u32_e32 v8, 0x840, v8
	s_cmp_eq_u32 s6, 0x280000
	s_waitcnt lgkmcnt(0)
	s_lshl_b32 s6, s52, 6
	ds_read2_b32 v[2:3], v41 offset1:33
	ds_read2_b32 v[4:5], v41 offset0:66 offset1:99
	ds_read2_b32 v[28:29], v41 offset0:132 offset1:165
	ds_read2_b32 v[30:31], v41 offset0:198 offset1:231
	s_and_b32 s54, s6, 0x700
	s_cmp_gt_u32 s52, 63
	s_cselect_b64 s[30:31], -1, 0
	s_waitcnt lgkmcnt(3)
	v_cvt_pk_bf16_f32 v2, v2, v3
	s_waitcnt lgkmcnt(2)
	v_cvt_pk_bf16_f32 v3, v4, v5
	s_waitcnt lgkmcnt(1)
	v_cvt_pk_bf16_f32 v4, v28, v29
	v_or_b32_e32 v28, s51, v40
	s_mov_b64 s[6:7], -1
	s_and_b64 vcc, exec, s[30:31]
	s_waitcnt lgkmcnt(0)
	v_cvt_pk_bf16_f32 v5, v30, v31
	s_cbranch_vccz .LBB0_39
	s_cmpk_lt_u32 s52, 0xc0
	v_mov_b32_e32 v8, v28
	s_cbranch_scc1 .LBB0_38
	v_and_b32_e32 v8, 0x67, v28
	s_cmpk_gt_u32 s52, 0xff
	v_or_b32_e32 v29, s54, v8
	s_cbranch_scc0 .LBB0_36
	s_add_i32 s6, s51, 0xffffe000
	s_lshr_b32 s6, s6, 3
	s_and_b32 s6, s6, 0x1fffff80
	v_add_u32_e32 v8, s6, v29
	v_add_u32_e32 v8, 0x2000, v8
	s_mov_b64 s[6:7], 0

; #define LAS __attribute__((address_space(3)))
; __device__ __forceinline__ unsigned pk2(float lo, float hi) { unsigned r; asm("v_cvt_pk_bf16_f32 %0, %1, %2" : "=v"(r) : "v"(lo), "v"(hi)); return r; }
; __device__ __forceinline__ int rowmap_ffn(int n) { if (n < DFF) return 256 * (n >> 7) + (n & 127); const int j = n - DFF; return 256 * (j >> 7) + 128 + (j & 127); }
; __device__ __forceinline__ void transpose_item(const float* W, int K, int N, bf16_t* WT, int mapk, LAS float* scr, int item, int lane) {
;     const int nblk = N / 32, kb = item / nblk, nb = item % nblk, k0 = 64 * kb, n0 = 32 * nb;
; #pragma unroll 8
;     for (int i = 0; i < 32; ++i) { const int kk = 2 * i + (lane >> 5); scr[kk * 33 + (lane & 31)] = __builtin_nontemporal_load(&W[(size_t)(k0 + kk) * N + n0 + (lane & 31)]); }
;     asm volatile("s_waitcnt lgkmcnt(0)" ::: "memory");
;     const int c = lane & 7;
; #pragma unroll
;     for (int j = 0; j < 4; ++j) { const int n = (lane >> 3) + 8 * j; const LAS float* s = scr + (8 * c) * 33 + n;
;         u32x4 o; o.x = pk2(s[0 * 33], s[1 * 33]); o.y = pk2(s[2 * 33], s[3 * 33]); o.z = pk2(s[4 * 33], s[5 * 33]); o.w = pk2(s[6 * 33], s[7 * 33]);
;         const int nn = n0 + n; const int row = mapk == 0 ? nn : (mapk == 1 ? rowmap_ffn(nn) : rowmap_win(nn));
;         *(u32x4*)(WT + (size_t)row * K + k0 + 8 * c) = o; }
;     asm volatile("s_waitcnt lgkmcnt(0)" ::: "memory");
; }
.LBB0_96:
	v_lshl_add_u64 v[54:55], v[38:39], 0, s[6:7]
	v_lshl_add_u64 v[56:57], v[36:37], 0, s[6:7]
	v_lshl_add_u64 v[58:59], v[34:35], 0, s[6:7]
	v_lshl_add_u64 v[60:61], v[32:33], 0, s[6:7]
	v_lshl_add_u64 v[62:63], v[30:31], 0, s[6:7]
	v_lshl_add_u64 v[64:65], v[28:29], 0, s[6:7]
	v_lshl_add_u64 v[66:67], v[4:5], 0, s[6:7]
	v_lshl_add_u64 v[68:69], v[2:3], 0, s[6:7]
	global_load_dword v80, v[54:55], off nt
	global_load_dword v81, v[56:57], off nt
	global_load_dword v82, v[58:59], off nt
	global_load_dword v83, v[60:61], off nt
	global_load_dword v84, v[62:63], off nt
	global_load_dword v85, v[64:65], off nt
	global_load_dword v86, v[66:67], off nt
	global_load_dword v87, v[68:69], off nt
	s_add_u32 s6, s6, 0x10000
	s_addc_u32 s7, s7, 0
	v_lshl_add_u64 v[54:55], v[38:39], 0, s[6:7]
	v_lshl_add_u64 v[56:57], v[36:37], 0, s[6:7]
	v_lshl_add_u64 v[58:59], v[34:35], 0, s[6:7]
	v_lshl_add_u64 v[60:61], v[32:33], 0, s[6:7]
	v_lshl_add_u64 v[62:63], v[30:31], 0, s[6:7]
	v_lshl_add_u64 v[64:65], v[28:29], 0, s[6:7]
	v_lshl_add_u64 v[66:67], v[4:5], 0, s[6:7]
	v_lshl_add_u64 v[68:69], v[2:3], 0, s[6:7]
	global_load_dword v88, v[54:55], off nt
	global_load_dword v89, v[56:57], off nt
	global_load_dword v90, v[58:59], off nt
	global_load_dword v91, v[60:61], off nt
	global_load_dword v92, v[62:63], off nt
	global_load_dword v93, v[64:65], off nt
	global_load_dword v94, v[66:67], off nt
	global_load_dword v95, v[68:69], off nt
	s_add_u32 s6, s6, 0x10000
	s_addc_u32 s7, s7, 0
	v_lshl_add_u64 v[54:55], v[38:39], 0, s[6:7]
	v_lshl_add_u64 v[56:57], v[36:37], 0, s[6:7]
	v_lshl_add_u64 v[58:59], v[34:35], 0, s[6:7]
	v_lshl_add_u64 v[60:61], v[32:33], 0, s[6:7]
	v_lshl_add_u64 v[62:63], v[30:31], 0, s[6:7]
	v_lshl_add_u64 v[64:65], v[28:29], 0, s[6:7]
	v_lshl_add_u64 v[66:67], v[4:5], 0, s[6:7]
	v_lshl_add_u64 v[68:69], v[2:3], 0, s[6:7]
	global_load_dword v96, v[54:55], off nt
	global_load_dword v97, v[56:57], off nt
	global_load_dword v98, v[58:59], off nt
	global_load_dword v99, v[60:61], off nt
	global_load_dword v100, v[62:63], off nt
	global_load_dword v101, v[64:65], off nt
	global_load_dword v102, v[66:67], off nt
	global_load_dword v103, v[68:69], off nt
	s_add_u32 s6, s6, 0x10000
	s_addc_u32 s7, s7, 0
	v_lshl_add_u64 v[54:55], v[38:39], 0, s[6:7]
	v_lshl_add_u64 v[56:57], v[36:37], 0, s[6:7]
	v_lshl_add_u64 v[58:59], v[34:35], 0, s[6:7]
	v_lshl_add_u64 v[60:61], v[32:33], 0, s[6:7]
	v_lshl_add_u64 v[62:63], v[30:31], 0, s[6:7]
	v_lshl_add_u64 v[64:65], v[28:29], 0, s[6:7]
	v_lshl_add_u64 v[66:67], v[4:5], 0, s[6:7]
	v_lshl_add_u64 v[68:69], v[2:3], 0, s[6:7]
	global_load_dword v104, v[54:55], off nt
	global_load_dword v105, v[56:57], off nt
	global_load_dword v106, v[58:59], off nt
	global_load_dword v107, v[60:61], off nt
	global_load_dword v108, v[62:63], off nt
	global_load_dword v109, v[64:65], off nt
	global_load_dword v110, v[66:67], off nt
	global_load_dword v111, v[68:69], off nt
	s_add_u32 s6, s6, 0x10000
	s_addc_u32 s7, s7, 0
	v_add_u32_e32 v54, 0x400, v8
	s_waitcnt vmcnt(30)
	ds_write2_b32 v8, v80, v81 offset1:66
	s_waitcnt vmcnt(28)
	ds_write2_b32 v8, v82, v83 offset0:132 offset1:198
	s_waitcnt vmcnt(26)
	ds_write2_b32 v54, v84, v85 offset0:8 offset1:74
	s_waitcnt vmcnt(24)
	ds_write2_b32 v54, v86, v87 offset0:140 offset1:206
	v_add_u32_e32 v8, 0x840, v8
	v_add_u32_e32 v54, 0x400, v8
	s_waitcnt vmcnt(22)
	ds_write2_b32 v8, v88, v89 offset1:66
	s_waitcnt vmcnt(20)
	ds_write2_b32 v8, v90, v91 offset0:132 offset1:198
	s_waitcnt vmcnt(18)
	ds_write2_b32 v54, v92, v93 offset0:8 offset1:74
	s_waitcnt vmcnt(16)
	ds_write2_b32 v54, v94, v95 offset0:140 offset1:206
	v_add_u32_e32 v8, 0x840, v8
	v_add_u32_e32 v54, 0x400, v8
	s_waitcnt vmcnt(14)
	ds_write2_b32 v8, v96, v97 offset1:66
	s_waitcnt vmcnt(12)
	ds_write2_b32 v8, v98, v99 offset0:132 offset1:198
	s_waitcnt vmcnt(10)
	ds_write2_b32 v54, v100, v101 offset0:8 offset1:74
	s_waitcnt vmcnt(8)
	ds_write2_b32 v54, v102, v103 offset0:140 offset1:206
	v_add_u32_e32 v8, 0x840, v8
	v_add_u32_e32 v54, 0x400, v8
	s_waitcnt vmcnt(6)
	ds_write2_b32 v8, v104, v105 offset1:66
	s_waitcnt vmcnt(4)
	ds_write2_b32 v8, v106, v107 offset0:132 offset1:198
	s_waitcnt vmcnt(2)
	ds_write2_b32 v54, v108, v109 offset0:8 offset1:74
	s_waitcnt vmcnt(0)
	ds_write2_b32 v54, v110, v111 offset0:140 offset1:206
	v_add_u32_e32 v8, 0x840, v8
	s_cmp_lg_u32 s6, 0x40000
	s_lshl_b32 s6, s3, 1
	s_lshl_b32 s7, s3, 5
	s_add_i32 s6, s6, 0x1c900
	s_and_b32 s7, s7, 0x3e0
	s_and_b32 s6, s6, 0x1ffc0
	s_waitcnt lgkmcnt(0)
	v_or_b32_e32 v8, s7, v40
	s_lshl_b32 s24, s6, 1
	ds_read2_b32 v[28:29], v41 offset0:33 offset1:41
	ds_read2_b32 v[30:31], v41 offset1:8
	ds_read2_b32 v[32:33], v41 offset0:66 offset1:74
	ds_read2_b32 v[34:35], v41 offset0:99 offset1:107
	ds_read2_b32 v[36:37], v41 offset0:132 offset1:140
	ds_read2_b32 v[38:39], v41 offset0:165 offset1:173
	ds_read2_b32 v[54:55], v41 offset0:198 offset1:206
	ds_read2_b32 v[56:57], v41 offset0:231 offset1:239
	v_mul_u32_u24_e32 v8, 0xb00, v8
	v_lshl_add_u64 v[58:59], v[20:21], 0, s[24:25]
	v_lshlrev_b32_e32 v8, 1, v8
	v_lshl_add_u64 v[60:61], v[58:59], 0, v[8:9]
	v_or_b32_e32 v8, s7, v42
	v_mul_u32_u24_e32 v8, 0xb00, v8
	s_waitcnt lgkmcnt(6)
	v_cvt_pk_bf16_f32 v2, v30, v28
	v_lshlrev_b32_e32 v8, 1, v8
	s_waitcnt lgkmcnt(4)
	v_cvt_pk_bf16_f32 v3, v32, v34
	s_waitcnt lgkmcnt(2)
	v_cvt_pk_bf16_f32 v4, v36, v38
	s_waitcnt lgkmcnt(0)
	v_cvt_pk_bf16_f32 v5, v54, v56
	global_store_dwordx4 v[60:61], v[2:5], off
	s_nop 1
	v_cvt_pk_bf16_f32 v2, v31, v29
	v_lshl_add_u64 v[28:29], v[58:59], 0, v[8:9]
	v_or_b32_e32 v8, s7, v43
	v_cvt_pk_bf16_f32 v3, v33, v35
	v_cvt_pk_bf16_f32 v4, v37, v39
	v_cvt_pk_bf16_f32 v5, v55, v57
	ds_read2_b32 v[30:31], v41 offset0:16 offset1:24
	ds_read2_b32 v[32:33], v41 offset0:49 offset1:57
	ds_read2_b32 v[34:35], v41 offset0:82 offset1:90
	ds_read2_b32 v[36:37], v41 offset0:115 offset1:123
	ds_read2_b32 v[38:39], v41 offset0:148 offset1:156
	ds_read2_b32 v[54:55], v41 offset0:181 offset1:189
	ds_read2_b32 v[56:57], v41 offset0:214 offset1:222
	ds_read2_b32 v[60:61], v41 offset0:247 offset1:255
	v_mul_u32_u24_e32 v8, 0xb00, v8
	v_lshlrev_b32_e32 v8, 1, v8
	global_store_dwordx4 v[28:29], v[2:5], off
	v_lshl_add_u64 v[28:29], v[58:59], 0, v[8:9]
	v_or_b32_e32 v8, s7, v44
	v_mul_u32_u24_e32 v8, 0xb00, v8
	v_lshlrev_b32_e32 v8, 1, v8
	s_waitcnt lgkmcnt(6)
	v_cvt_pk_bf16_f32 v2, v30, v32
	s_waitcnt lgkmcnt(4)
	v_cvt_pk_bf16_f32 v3, v34, v36
	s_waitcnt lgkmcnt(2)
	v_cvt_pk_bf16_f32 v4, v38, v54
	s_waitcnt lgkmcnt(0)
	v_cvt_pk_bf16_f32 v5, v56, v60
	global_store_dwordx4 v[28:29], v[2:5], off
	v_lshl_add_u64 v[28:29], v[58:59], 0, v[8:9]
	s_nop 0
	v_cvt_pk_bf16_f32 v2, v31, v33
	v_cvt_pk_bf16_f32 v3, v35, v37
	v_cvt_pk_bf16_f32 v4, v39, v55
	v_cvt_pk_bf16_f32 v5, v57, v61
	global_store_dwordx4 v[28:29], v[2:5], off
	s_waitcnt lgkmcnt(0)

; #define LAS __attribute__((address_space(3)))
; __device__ __forceinline__ unsigned pk2(float lo, float hi) { unsigned r; asm("v_cvt_pk_bf16_f32 %0, %1, %2" : "=v"(r) : "v"(lo), "v"(hi)); return r; }
; __device__ __forceinline__ int rowmap_ffn(int n) { if (n < DFF) return 256 * (n >> 7) + (n & 127); const int j = n - DFF; return 256 * (j >> 7) + 128 + (j & 127); }
; __device__ __forceinline__ void transpose_item(const float* W, int K, int N, bf16_t* WT, int mapk, LAS float* scr, int item, int lane) {
;     const int nblk = N / 32, kb = item / nblk, nb = item % nblk, k0 = 64 * kb, n0 = 32 * nb;
; #pragma unroll 8
;     for (int i = 0; i < 32; ++i) { const int kk = 2 * i + (lane >> 5); scr[kk * 33 + (lane & 31)] = __builtin_nontemporal_load(&W[(size_t)(k0 + kk) * N + n0 + (lane & 31)]); }
;     asm volatile("s_waitcnt lgkmcnt(0)" ::: "memory");
;     const int c = lane & 7;
; #pragma unroll
;     for (int j = 0; j < 4; ++j) { const int n = (lane >> 3) + 8 * j; const LAS float* s = scr + (8 * c) * 33 + n;
;         u32x4 o; o.x = pk2(s[0 * 33], s[1 * 33]); o.y = pk2(s[2 * 33], s[3 * 33]); o.z = pk2(s[4 * 33], s[5 * 33]); o.w = pk2(s[6 * 33], s[7 * 33]);
;         const int nn = n0 + n; const int row = mapk == 0 ? nn : (mapk == 1 ? rowmap_ffn(nn) : rowmap_win(nn));
;         *(u32x4*)(WT + (size_t)row * K + k0 + 8 * c) = o; }
;     asm volatile("s_waitcnt lgkmcnt(0)" ::: "memory");
; }
; __global__ void __launch_bounds__(512, 2) fwd_megakernel(Params Parg) {
;     ...
;             if (r < I_FO) { transpose_item(IN(8), DFF, D, WSP(bf16_t, WS_WFFN1OUT), 0, scr, r, lane); continue; } r -= I_FO;
;             if (r < I_FO) { transpose_item(IN(23), DFF, D, WSP(bf16_t, WS_WFFN2OUT), 0, scr, r, lane); continue; } r -= I_FO;
.LBB0_101:
	v_lshl_add_u64 v[54:55], v[38:39], 0, s[6:7]
	v_lshl_add_u64 v[56:57], v[36:37], 0, s[6:7]
	v_lshl_add_u64 v[58:59], v[34:35], 0, s[6:7]
	v_lshl_add_u64 v[60:61], v[32:33], 0, s[6:7]
	v_lshl_add_u64 v[62:63], v[30:31], 0, s[6:7]
	v_lshl_add_u64 v[64:65], v[28:29], 0, s[6:7]
	v_lshl_add_u64 v[66:67], v[4:5], 0, s[6:7]
	v_lshl_add_u64 v[68:69], v[2:3], 0, s[6:7]
	global_load_dword v80, v[54:55], off nt
	global_load_dword v81, v[56:57], off nt
	global_load_dword v82, v[58:59], off nt
	global_load_dword v83, v[60:61], off nt
	global_load_dword v84, v[62:63], off nt
	global_load_dword v85, v[64:65], off nt
	global_load_dword v86, v[66:67], off nt
	global_load_dword v87, v[68:69], off nt
	s_add_u32 s6, s6, 0x10000
	s_addc_u32 s7, s7, 0
	v_lshl_add_u64 v[54:55], v[38:39], 0, s[6:7]
	v_lshl_add_u64 v[56:57], v[36:37], 0, s[6:7]
	v_lshl_add_u64 v[58:59], v[34:35], 0, s[6:7]
	v_lshl_add_u64 v[60:61], v[32:33], 0, s[6:7]
	v_lshl_add_u64 v[62:63], v[30:31], 0, s[6:7]
	v_lshl_add_u64 v[64:65], v[28:29], 0, s[6:7]
	v_lshl_add_u64 v[66:67], v[4:5], 0, s[6:7]
	v_lshl_add_u64 v[68:69], v[2:3], 0, s[6:7]
	global_load_dword v88, v[54:55], off nt
	global_load_dword v89, v[56:57], off nt
	global_load_dword v90, v[58:59], off nt
	global_load_dword v91, v[60:61], off nt
	global_load_dword v92, v[62:63], off nt
	global_load_dword v93, v[64:65], off nt
	global_load_dword v94, v[66:67], off nt
	global_load_dword v95, v[68:69], off nt
	s_add_u32 s6, s6, 0x10000
	s_addc_u32 s7, s7, 0
	v_lshl_add_u64 v[54:55], v[38:39], 0, s[6:7]
	v_lshl_add_u64 v[56:57], v[36:37], 0, s[6:7]
	v_lshl_add_u64 v[58:59], v[34:35], 0, s[6:7]
	v_lshl_add_u64 v[60:61], v[32:33], 0, s[6:7]
	v_lshl_add_u64 v[62:63], v[30:31], 0, s[6:7]
	v_lshl_add_u64 v[64:65], v[28:29], 0, s[6:7]
	v_lshl_add_u64 v[66:67], v[4:5], 0, s[6:7]
	v_lshl_add_u64 v[68:69], v[2:3], 0, s[6:7]
	global_load_dword v96, v[54:55], off nt
	global_load_dword v97, v[56:57], off nt
	global_load_dword v98, v[58:59], off nt
	global_load_dword v99, v[60:61], off nt
	global_load_dword v100, v[62:63], off nt
	global_load_dword v101, v[64:65], off nt
	global_load_dword v102, v[66:67], off nt
	global_load_dword v103, v[68:69], off nt
	s_add_u32 s6, s6, 0x10000
	s_addc_u32 s7, s7, 0
	v_lshl_add_u64 v[54:55], v[38:39], 0, s[6:7]
	v_lshl_add_u64 v[56:57], v[36:37], 0, s[6:7]
	v_lshl_add_u64 v[58:59], v[34:35], 0, s[6:7]
	v_lshl_add_u64 v[60:61], v[32:33], 0, s[6:7]
	v_lshl_add_u64 v[62:63], v[30:31], 0, s[6:7]
	v_lshl_add_u64 v[64:65], v[28:29], 0, s[6:7]
	v_lshl_add_u64 v[66:67], v[4:5], 0, s[6:7]
	v_lshl_add_u64 v[68:69], v[2:3], 0, s[6:7]
	global_load_dword v104, v[54:55], off nt
	global_load_dword v105, v[56:57], off nt
	global_load_dword v106, v[58:59], off nt
	global_load_dword v107, v[60:61], off nt
	global_load_dword v108, v[62:63], off nt
	global_load_dword v109, v[64:65], off nt
	global_load_dword v110, v[66:67], off nt
	global_load_dword v111, v[68:69], off nt
	s_add_u32 s6, s6, 0x10000
	s_addc_u32 s7, s7, 0
	v_add_u32_e32 v54, 0x400, v8
	s_waitcnt vmcnt(30)
	ds_write2_b32 v8, v80, v81 offset1:66
	s_waitcnt vmcnt(28)
	ds_write2_b32 v8, v82, v83 offset0:132 offset1:198
	s_waitcnt vmcnt(26)
	ds_write2_b32 v54, v84, v85 offset0:8 offset1:74
	s_waitcnt vmcnt(24)
	ds_write2_b32 v54, v86, v87 offset0:140 offset1:206
	v_add_u32_e32 v8, 0x840, v8
	v_add_u32_e32 v54, 0x400, v8
	s_waitcnt vmcnt(22)
	ds_write2_b32 v8, v88, v89 offset1:66
	s_waitcnt vmcnt(20)
	ds_write2_b32 v8, v90, v91 offset0:132 offset1:198
	s_waitcnt vmcnt(18)
	ds_write2_b32 v54, v92, v93 offset0:8 offset1:74
	s_waitcnt vmcnt(16)
	ds_write2_b32 v54, v94, v95 offset0:140 offset1:206
	v_add_u32_e32 v8, 0x840, v8
	v_add_u32_e32 v54, 0x400, v8
	s_waitcnt vmcnt(14)
	ds_write2_b32 v8, v96, v97 offset1:66
	s_waitcnt vmcnt(12)
	ds_write2_b32 v8, v98, v99 offset0:132 offset1:198
	s_waitcnt vmcnt(10)
	ds_write2_b32 v54, v100, v101 offset0:8 offset1:74
	s_waitcnt vmcnt(8)
	ds_write2_b32 v54, v102, v103 offset0:140 offset1:206
	v_add_u32_e32 v8, 0x840, v8
	v_add_u32_e32 v54, 0x400, v8
	s_waitcnt vmcnt(6)
	ds_write2_b32 v8, v104, v105 offset1:66
	s_waitcnt vmcnt(4)
	ds_write2_b32 v8, v106, v107 offset0:132 offset1:198
	s_waitcnt vmcnt(2)
	ds_write2_b32 v54, v108, v109 offset0:8 offset1:74
	s_waitcnt vmcnt(0)
	ds_write2_b32 v54, v110, v111 offset0:140 offset1:206
	v_add_u32_e32 v8, 0x840, v8
	s_cmp_lg_u32 s6, 0x40000
	s_lshl_b32 s6, s3, 1
	s_lshl_b32 s7, s3, 5
	s_add_i32 s6, s6, 0x1d400
	s_and_b32 s7, s7, 0x3e0
	s_and_b32 s6, s6, 0x1ffc0
	s_waitcnt lgkmcnt(0)
	v_or_b32_e32 v8, s7, v40
	s_lshl_b32 s24, s6, 1
	ds_read2_b32 v[28:29], v41 offset0:33 offset1:41
	ds_read2_b32 v[30:31], v41 offset1:8
	ds_read2_b32 v[32:33], v41 offset0:66 offset1:74
	ds_read2_b32 v[34:35], v41 offset0:99 offset1:107
	ds_read2_b32 v[36:37], v41 offset0:132 offset1:140
	ds_read2_b32 v[38:39], v41 offset0:165 offset1:173
	ds_read2_b32 v[54:55], v41 offset0:198 offset1:206
	ds_read2_b32 v[56:57], v41 offset0:231 offset1:239
	v_mul_u32_u24_e32 v8, 0xb00, v8
	v_lshl_add_u64 v[58:59], v[22:23], 0, s[24:25]
	v_lshlrev_b32_e32 v8, 1, v8
	v_lshl_add_u64 v[60:61], v[58:59], 0, v[8:9]
	v_or_b32_e32 v8, s7, v42
	v_mul_u32_u24_e32 v8, 0xb00, v8
	s_waitcnt lgkmcnt(6)
	v_cvt_pk_bf16_f32 v2, v30, v28
	v_lshlrev_b32_e32 v8, 1, v8
	s_waitcnt lgkmcnt(4)
	v_cvt_pk_bf16_f32 v3, v32, v34
	s_waitcnt lgkmcnt(2)
	v_cvt_pk_bf16_f32 v4, v36, v38
	s_waitcnt lgkmcnt(0)
	v_cvt_pk_bf16_f32 v5, v54, v56
	global_store_dwordx4 v[60:61], v[2:5], off
	s_nop 1
	v_cvt_pk_bf16_f32 v2, v31, v29
	v_lshl_add_u64 v[28:29], v[58:59], 0, v[8:9]
	v_or_b32_e32 v8, s7, v43
	v_cvt_pk_bf16_f32 v3, v33, v35
	v_cvt_pk_bf16_f32 v4, v37, v39
	v_cvt_pk_bf16_f32 v5, v55, v57
	ds_read2_b32 v[30:31], v41 offset0:16 offset1:24
	ds_read2_b32 v[32:33], v41 offset0:49 offset1:57
	ds_read2_b32 v[34:35], v41 offset0:82 offset1:90
	ds_read2_b32 v[36:37], v41 offset0:115 offset1:123
	ds_read2_b32 v[38:39], v41 offset0:148 offset1:156
	ds_read2_b32 v[54:55], v41 offset0:181 offset1:189
	ds_read2_b32 v[56:57], v41 offset0:214 offset1:222
	ds_read2_b32 v[60:61], v41 offset0:247 offset1:255
	v_mul_u32_u24_e32 v8, 0xb00, v8
	v_lshlrev_b32_e32 v8, 1, v8
	global_store_dwordx4 v[28:29], v[2:5], off
	v_lshl_add_u64 v[28:29], v[58:59], 0, v[8:9]
	v_or_b32_e32 v8, s7, v44
	v_mul_u32_u24_e32 v8, 0xb00, v8
	v_lshlrev_b32_e32 v8, 1, v8
	s_waitcnt lgkmcnt(6)
	v_cvt_pk_bf16_f32 v2, v30, v32
	s_waitcnt lgkmcnt(4)
	v_cvt_pk_bf16_f32 v3, v34, v36
	s_waitcnt lgkmcnt(2)
	v_cvt_pk_bf16_f32 v4, v38, v54
	s_waitcnt lgkmcnt(0)
	v_cvt_pk_bf16_f32 v5, v56, v60
	global_store_dwordx4 v[28:29], v[2:5], off
	v_lshl_add_u64 v[28:29], v[58:59], 0, v[8:9]
	s_nop 0
	v_cvt_pk_bf16_f32 v2, v31, v33
	v_cvt_pk_bf16_f32 v3, v35, v37
	v_cvt_pk_bf16_f32 v4, v39, v55
	v_cvt_pk_bf16_f32 v5, v57, v61
	global_store_dwordx4 v[28:29], v[2:5], off
	s_waitcnt lgkmcnt(0)

; #define LAS __attribute__((address_space(3)))
; __device__ __forceinline__ unsigned pk2(float lo, float hi) { unsigned r; asm("v_cvt_pk_bf16_f32 %0, %1, %2" : "=v"(r) : "v"(lo), "v"(hi)); return r; }
; __device__ __forceinline__ int rowmap_ffn(int n) { if (n < DFF) return 256 * (n >> 7) + (n & 127); const int j = n - DFF; return 256 * (j >> 7) + 128 + (j & 127); }
; __device__ __forceinline__ void transpose_item(const float* W, int K, int N, bf16_t* WT, int mapk, LAS float* scr, int item, int lane) {
;     const int nblk = N / 32, kb = item / nblk, nb = item % nblk, k0 = 64 * kb, n0 = 32 * nb;
; #pragma unroll 8
;     for (int i = 0; i < 32; ++i) { const int kk = 2 * i + (lane >> 5); scr[kk * 33 + (lane & 31)] = __builtin_nontemporal_load(&W[(size_t)(k0 + kk) * N + n0 + (lane & 31)]); }
;     asm volatile("s_waitcnt lgkmcnt(0)" ::: "memory");
;     const int c = lane & 7;
; #pragma unroll
;     for (int j = 0; j < 4; ++j) { const int n = (lane >> 3) + 8 * j; const LAS float* s = scr + (8 * c) * 33 + n;
;         u32x4 o; o.x = pk2(s[0 * 33], s[1 * 33]); o.y = pk2(s[2 * 33], s[3 * 33]); o.z = pk2(s[4 * 33], s[5 * 33]); o.w = pk2(s[6 * 33], s[7 * 33]);
;         const int nn = n0 + n; const int row = mapk == 0 ? nn : (mapk == 1 ? rowmap_ffn(nn) : rowmap_win(nn));
;         *(u32x4*)(WT + (size_t)row * K + k0 + 8 * c) = o; }
;     asm volatile("s_waitcnt lgkmcnt(0)" ::: "memory");
; }
; __global__ void __launch_bounds__(512, 2) fwd_megakernel(Params Parg) {
;     ...
;             if (r < I_FI) { transpose_item(IN(7), D, 2 * DFF, WSP(bf16_t, WS_WFFN1IN), 1, scr, r, lane); continue; } r -= I_FI;
.LBB0_106:
	v_lshl_add_u64 v[54:55], v[38:39], 0, s[6:7]
	v_lshl_add_u64 v[56:57], v[36:37], 0, s[6:7]
	v_lshl_add_u64 v[58:59], v[34:35], 0, s[6:7]
	v_lshl_add_u64 v[60:61], v[32:33], 0, s[6:7]
	v_lshl_add_u64 v[62:63], v[30:31], 0, s[6:7]
	v_lshl_add_u64 v[64:65], v[28:29], 0, s[6:7]
	v_lshl_add_u64 v[66:67], v[4:5], 0, s[6:7]
	v_lshl_add_u64 v[68:69], v[2:3], 0, s[6:7]
	global_load_dword v80, v[54:55], off nt
	global_load_dword v81, v[56:57], off nt
	global_load_dword v82, v[58:59], off nt
	global_load_dword v83, v[60:61], off nt
	global_load_dword v84, v[62:63], off nt
	global_load_dword v85, v[64:65], off nt
	global_load_dword v86, v[66:67], off nt
	global_load_dword v87, v[68:69], off nt
	s_add_u32 s6, s6, 0x58000
	s_addc_u32 s7, s7, 0
	v_lshl_add_u64 v[54:55], v[38:39], 0, s[6:7]
	v_lshl_add_u64 v[56:57], v[36:37], 0, s[6:7]
	v_lshl_add_u64 v[58:59], v[34:35], 0, s[6:7]
	v_lshl_add_u64 v[60:61], v[32:33], 0, s[6:7]
	v_lshl_add_u64 v[62:63], v[30:31], 0, s[6:7]
	v_lshl_add_u64 v[64:65], v[28:29], 0, s[6:7]
	v_lshl_add_u64 v[66:67], v[4:5], 0, s[6:7]
	v_lshl_add_u64 v[68:69], v[2:3], 0, s[6:7]
	global_load_dword v88, v[54:55], off nt
	global_load_dword v89, v[56:57], off nt
	global_load_dword v90, v[58:59], off nt
	global_load_dword v91, v[60:61], off nt
	global_load_dword v92, v[62:63], off nt
	global_load_dword v93, v[64:65], off nt
	global_load_dword v94, v[66:67], off nt
	global_load_dword v95, v[68:69], off nt
	s_add_u32 s6, s6, 0x58000
	s_addc_u32 s7, s7, 0
	v_lshl_add_u64 v[54:55], v[38:39], 0, s[6:7]
	v_lshl_add_u64 v[56:57], v[36:37], 0, s[6:7]
	v_lshl_add_u64 v[58:59], v[34:35], 0, s[6:7]
	v_lshl_add_u64 v[60:61], v[32:33], 0, s[6:7]
	v_lshl_add_u64 v[62:63], v[30:31], 0, s[6:7]
	v_lshl_add_u64 v[64:65], v[28:29], 0, s[6:7]
	v_lshl_add_u64 v[66:67], v[4:5], 0, s[6:7]
	v_lshl_add_u64 v[68:69], v[2:3], 0, s[6:7]
	global_load_dword v96, v[54:55], off nt
	global_load_dword v97, v[56:57], off nt
	global_load_dword v98, v[58:59], off nt
	global_load_dword v99, v[60:61], off nt
	global_load_dword v100, v[62:63], off nt
	global_load_dword v101, v[64:65], off nt
	global_load_dword v102, v[66:67], off nt
	global_load_dword v103, v[68:69], off nt
	s_add_u32 s6, s6, 0x58000
	s_addc_u32 s7, s7, 0
	v_lshl_add_u64 v[54:55], v[38:39], 0, s[6:7]
	v_lshl_add_u64 v[56:57], v[36:37], 0, s[6:7]
	v_lshl_add_u64 v[58:59], v[34:35], 0, s[6:7]
	v_lshl_add_u64 v[60:61], v[32:33], 0, s[6:7]
	v_lshl_add_u64 v[62:63], v[30:31], 0, s[6:7]
	v_lshl_add_u64 v[64:65], v[28:29], 0, s[6:7]
	v_lshl_add_u64 v[66:67], v[4:5], 0, s[6:7]
	v_lshl_add_u64 v[68:69], v[2:3], 0, s[6:7]
	global_load_dword v104, v[54:55], off nt
	global_load_dword v105, v[56:57], off nt
	global_load_dword v106, v[58:59], off nt
	global_load_dword v107, v[60:61], off nt
	global_load_dword v108, v[62:63], off nt
	global_load_dword v109, v[64:65], off nt
	global_load_dword v110, v[66:67], off nt
	global_load_dword v111, v[68:69], off nt
	s_add_u32 s6, s6, 0x58000
	s_addc_u32 s7, s7, 0
	v_add_u32_e32 v62, 0x400, v8
	s_waitcnt vmcnt(30)
	ds_write2_b32 v8, v80, v81 offset1:66
	s_waitcnt vmcnt(28)
	ds_write2_b32 v8, v82, v83 offset0:132 offset1:198
	s_waitcnt vmcnt(26)
	ds_write2_b32 v62, v84, v85 offset0:8 offset1:74
	s_waitcnt vmcnt(24)
	ds_write2_b32 v62, v86, v87 offset0:140 offset1:206
	v_add_u32_e32 v8, 0x840, v8
	v_add_u32_e32 v62, 0x400, v8
	s_waitcnt vmcnt(22)
	ds_write2_b32 v8, v88, v89 offset1:66
	s_waitcnt vmcnt(20)
	ds_write2_b32 v8, v90, v91 offset0:132 offset1:198
	s_waitcnt vmcnt(18)
	ds_write2_b32 v62, v92, v93 offset0:8 offset1:74
	s_waitcnt vmcnt(16)
	ds_write2_b32 v62, v94, v95 offset0:140 offset1:206
	v_add_u32_e32 v8, 0x840, v8
	v_add_u32_e32 v62, 0x400, v8
	s_waitcnt vmcnt(14)
	ds_write2_b32 v8, v96, v97 offset1:66
	s_waitcnt vmcnt(12)
	ds_write2_b32 v8, v98, v99 offset0:132 offset1:198
	s_waitcnt vmcnt(10)
	ds_write2_b32 v62, v100, v101 offset0:8 offset1:74
	s_waitcnt vmcnt(8)
	ds_write2_b32 v62, v102, v103 offset0:140 offset1:206
	v_add_u32_e32 v8, 0x840, v8
	v_add_u32_e32 v62, 0x400, v8
	s_waitcnt vmcnt(6)
	ds_write2_b32 v8, v104, v105 offset1:66
	s_waitcnt vmcnt(4)
	ds_write2_b32 v8, v106, v107 offset0:132 offset1:198
	s_waitcnt vmcnt(2)
	ds_write2_b32 v62, v108, v109 offset0:8 offset1:74
	s_waitcnt vmcnt(0)
	ds_write2_b32 v62, v110, v111 offset0:140 offset1:206
	v_add_u32_e32 v8, 0x840, v8
	s_cmp_eq_u32 s6, 0x160000
	s_waitcnt lgkmcnt(0)
	ds_read2_b32 v[2:3], v41 offset1:33
	ds_read2_b32 v[4:5], v41 offset0:66 offset1:99
	ds_read2_b32 v[28:29], v41 offset0:132 offset1:165
	ds_read2_b32 v[30:31], v41 offset0:198 offset1:231
	s_and_b32 s50, 0xffff, s31
	s_and_b32 s6, 0xffff, s30
	s_cmpk_gt_u32 s6, 0x57
	v_or_b32_e32 v8, s50, v40
	s_cselect_b64 s[30:31], -1, 0
	s_waitcnt lgkmcnt(3)
	v_cvt_pk_bf16_f32 v2, v2, v3
	s_waitcnt lgkmcnt(2)
	v_cvt_pk_bf16_f32 v3, v4, v5
	s_waitcnt lgkmcnt(1)
	v_cvt_pk_bf16_f32 v4, v28, v29
	v_lshlrev_b32_e32 v28, 1, v8
	s_mov_b64 s[6:7], -1
	s_and_b64 vcc, exec, s[30:31]
	v_and_b32_e32 v29, 0x67, v8
	s_waitcnt lgkmcnt(0)
	v_cvt_pk_bf16_f32 v5, v30, v31
	s_cbranch_vccz .LBB0_109
	v_add_u32_e32 v8, 0x7fffea00, v28
	v_and_b32_e32 v8, 0x7fffff00, v8
	v_or3_b32 v8, v29, v8, s46
	s_mov_b64 s[6:7], 0

; #define LAS __attribute__((address_space(3)))
; __device__ __forceinline__ void transpose_item(const float* W, int K, int N, bf16_t* WT, int mapk, LAS float* scr, int item, int lane) {
;     const int nblk = N / 32, kb = item / nblk, nb = item % nblk, k0 = 64 * kb, n0 = 32 * nb;
; #pragma unroll 8
;     for (int i = 0; i < 32; ++i) { const int kk = 2 * i + (lane >> 5); scr[kk * 33 + (lane & 31)] = __builtin_nontemporal_load(&W[(size_t)(k0 + kk) * N + n0 + (lane & 31)]); }
;     asm volatile("s_waitcnt lgkmcnt(0)" ::: "memory");
; __global__ void __launch_bounds__(512, 2) fwd_megakernel(Params Parg) {
;     ...
;             if (r < I_FI) { transpose_item(IN(22), D, 2 * DFF, WSP(bf16_t, WS_WFFN2IN), 1, scr, r, lane); continue; } r -= I_FI;
.LBB0_127:
	v_lshl_add_u64 v[54:55], v[38:39], 0, s[34:35]
	v_lshl_add_u64 v[56:57], v[36:37], 0, s[34:35]
	v_lshl_add_u64 v[58:59], v[34:35], 0, s[34:35]
	v_lshl_add_u64 v[60:61], v[32:33], 0, s[34:35]
	v_lshl_add_u64 v[62:63], v[30:31], 0, s[34:35]
	v_lshl_add_u64 v[64:65], v[28:29], 0, s[34:35]
	v_lshl_add_u64 v[66:67], v[4:5], 0, s[34:35]
	v_lshl_add_u64 v[68:69], v[2:3], 0, s[34:35]
	global_load_dword v80, v[54:55], off nt
	global_load_dword v81, v[56:57], off nt
	global_load_dword v82, v[58:59], off nt
	global_load_dword v83, v[60:61], off nt
	global_load_dword v84, v[62:63], off nt
	global_load_dword v85, v[64:65], off nt
	global_load_dword v86, v[66:67], off nt
	global_load_dword v87, v[68:69], off nt
	s_add_u32 s34, s34, 0x58000
	s_addc_u32 s35, s35, 0
	v_lshl_add_u64 v[54:55], v[38:39], 0, s[34:35]
	v_lshl_add_u64 v[56:57], v[36:37], 0, s[34:35]
	v_lshl_add_u64 v[58:59], v[34:35], 0, s[34:35]
	v_lshl_add_u64 v[60:61], v[32:33], 0, s[34:35]
	v_lshl_add_u64 v[62:63], v[30:31], 0, s[34:35]
	v_lshl_add_u64 v[64:65], v[28:29], 0, s[34:35]
	v_lshl_add_u64 v[66:67], v[4:5], 0, s[34:35]
	v_lshl_add_u64 v[68:69], v[2:3], 0, s[34:35]
	global_load_dword v88, v[54:55], off nt
	global_load_dword v89, v[56:57], off nt
	global_load_dword v90, v[58:59], off nt
	global_load_dword v91, v[60:61], off nt
	global_load_dword v92, v[62:63], off nt
	global_load_dword v93, v[64:65], off nt
	global_load_dword v94, v[66:67], off nt
	global_load_dword v95, v[68:69], off nt
	s_add_u32 s34, s34, 0x58000
	s_addc_u32 s35, s35, 0
	v_lshl_add_u64 v[54:55], v[38:39], 0, s[34:35]
	v_lshl_add_u64 v[56:57], v[36:37], 0, s[34:35]
	v_lshl_add_u64 v[58:59], v[34:35], 0, s[34:35]
	v_lshl_add_u64 v[60:61], v[32:33], 0, s[34:35]
	v_lshl_add_u64 v[62:63], v[30:31], 0, s[34:35]
	v_lshl_add_u64 v[64:65], v[28:29], 0, s[34:35]
	v_lshl_add_u64 v[66:67], v[4:5], 0, s[34:35]
	v_lshl_add_u64 v[68:69], v[2:3], 0, s[34:35]
	global_load_dword v96, v[54:55], off nt
	global_load_dword v97, v[56:57], off nt
	global_load_dword v98, v[58:59], off nt
	global_load_dword v99, v[60:61], off nt
	global_load_dword v100, v[62:63], off nt
	global_load_dword v101, v[64:65], off nt
	global_load_dword v102, v[66:67], off nt
	global_load_dword v103, v[68:69], off nt
	s_add_u32 s34, s34, 0x58000
	s_addc_u32 s35, s35, 0
	v_lshl_add_u64 v[54:55], v[38:39], 0, s[34:35]
	v_lshl_add_u64 v[56:57], v[36:37], 0, s[34:35]
	v_lshl_add_u64 v[58:59], v[34:35], 0, s[34:35]
	v_lshl_add_u64 v[60:61], v[32:33], 0, s[34:35]
	v_lshl_add_u64 v[62:63], v[30:31], 0, s[34:35]
	v_lshl_add_u64 v[64:65], v[28:29], 0, s[34:35]
	v_lshl_add_u64 v[66:67], v[4:5], 0, s[34:35]
	v_lshl_add_u64 v[68:69], v[2:3], 0, s[34:35]
	global_load_dword v104, v[54:55], off nt
	global_load_dword v105, v[56:57], off nt
	global_load_dword v106, v[58:59], off nt
	global_load_dword v107, v[60:61], off nt
	global_load_dword v108, v[62:63], off nt
	global_load_dword v109, v[64:65], off nt
	global_load_dword v110, v[66:67], off nt
	global_load_dword v111, v[68:69], off nt
	s_add_u32 s34, s34, 0x58000
	s_addc_u32 s35, s35, 0
	v_add_u32_e32 v62, 0x400, v8
	s_waitcnt vmcnt(30)
	ds_write2_b32 v8, v80, v81 offset1:66
	s_waitcnt vmcnt(28)
	ds_write2_b32 v8, v82, v83 offset0:132 offset1:198
	s_waitcnt vmcnt(26)
	ds_write2_b32 v62, v84, v85 offset0:8 offset1:74
	s_waitcnt vmcnt(24)
	ds_write2_b32 v62, v86, v87 offset0:140 offset1:206
	v_add_u32_e32 v8, 0x840, v8
	v_add_u32_e32 v62, 0x400, v8
	s_waitcnt vmcnt(22)
	ds_write2_b32 v8, v88, v89 offset1:66
	s_waitcnt vmcnt(20)
	ds_write2_b32 v8, v90, v91 offset0:132 offset1:198
	s_waitcnt vmcnt(18)
	ds_write2_b32 v62, v92, v93 offset0:8 offset1:74
	s_waitcnt vmcnt(16)
	ds_write2_b32 v62, v94, v95 offset0:140 offset1:206
	v_add_u32_e32 v8, 0x840, v8
	v_add_u32_e32 v62, 0x400, v8
	s_waitcnt vmcnt(14)
	ds_write2_b32 v8, v96, v97 offset1:66
	s_waitcnt vmcnt(12)
	ds_write2_b32 v8, v98, v99 offset0:132 offset1:198
	s_waitcnt vmcnt(10)
	ds_write2_b32 v62, v100, v101 offset0:8 offset1:74
	s_waitcnt vmcnt(8)
	ds_write2_b32 v62, v102, v103 offset0:140 offset1:206
	v_add_u32_e32 v8, 0x840, v8
	v_add_u32_e32 v62, 0x400, v8
	s_waitcnt vmcnt(6)
	ds_write2_b32 v8, v104, v105 offset1:66
	s_waitcnt vmcnt(4)
; #define LAS __attribute__((address_space(3)))
; __device__ __forceinline__ unsigned pk2(float lo, float hi) { unsigned r; asm("v_cvt_pk_bf16_f32 %0, %1, %2" : "=v"(r) : "v"(lo), "v"(hi)); return r; }
; __device__ __forceinline__ int rowmap_ffn(int n) { if (n < DFF) return 256 * (n >> 7) + (n & 127); const int j = n - DFF; return 256 * (j >> 7) + 128 + (j & 127); }
; __device__ __forceinline__ void transpose_item(const float* W, int K, int N, bf16_t* WT, int mapk, LAS float* scr, int item, int lane) {
;     ...
;     for (int i = 0; i < 32; ++i) { const int kk = 2 * i + (lane >> 5); scr[kk * 33 + (lane & 31)] = __builtin_nontemporal_load(&W[(size_t)(k0 + kk) * N + n0 + (lane & 31)]); }
;     asm volatile("s_waitcnt lgkmcnt(0)" ::: "memory");
;     const int c = lane & 7;
; #pragma unroll
;     for (int j = 0; j < 4; ++j) { const int n = (lane >> 3) + 8 * j; const LAS float* s = scr + (8 * c) * 33 + n;
;         u32x4 o; o.x = pk2(s[0 * 33], s[1 * 33]); o.y = pk2(s[2 * 33], s[3 * 33]); o.z = pk2(s[4 * 33], s[5 * 33]); o.w = pk2(s[6 * 33], s[7 * 33]);
;         const int nn = n0 + n; const int row = mapk == 0 ? nn : (mapk == 1 ? rowmap_ffn(nn) : rowmap_win(nn));
;         *(u32x4*)(WT + (size_t)row * K + k0 + 8 * c) = o; }
;     asm volatile("s_waitcnt lgkmcnt(0)" ::: "memory");
; }
	ds_write2_b32 v8, v106, v107 offset0:132 offset1:198
	s_waitcnt vmcnt(2)
	ds_write2_b32 v62, v108, v109 offset0:8 offset1:74
	s_waitcnt vmcnt(0)
	ds_write2_b32 v62, v110, v111 offset0:140 offset1:206
	v_add_u32_e32 v8, 0x840, v8
	s_cmp_eq_u32 s34, 0x160000
	s_waitcnt lgkmcnt(0)
	ds_read2_b32 v[2:3], v41 offset1:33
	ds_read2_b32 v[4:5], v41 offset0:66 offset1:99
	ds_read2_b32 v[28:29], v41 offset0:132 offset1:165
	ds_read2_b32 v[30:31], v41 offset0:198 offset1:231
	s_waitcnt lgkmcnt(3)
	v_cvt_pk_bf16_f32 v2, v2, v3
	s_waitcnt lgkmcnt(2)
	v_cvt_pk_bf16_f32 v3, v4, v5
	s_waitcnt lgkmcnt(1)
	v_cvt_pk_bf16_f32 v4, v28, v29
	v_or_b32_e32 v28, s6, v40
	v_cmp_lt_i32_e32 vcc, s41, v28
	v_lshlrev_b32_e32 v8, 1, v28
	v_and_b32_e32 v28, 0x67, v28
	s_waitcnt lgkmcnt(0)
	v_cvt_pk_bf16_f32 v5, v30, v31
	s_and_saveexec_b64 s[34:35], vcc
	s_xor_b64 s[34:35], exec, s[34:35]
	v_add_u32_e32 v8, 0x7fffea00, v8
	v_and_b32_e32 v8, 0x7fffff00, v8
	v_or3_b32 v30, v28, v8, s46
	s_andn2_saveexec_b64 s[34:35], s[34:35]
	v_and_or_b32 v30, v8, s48, v28
	s_or_b64 exec, exec, s[34:35]
	s_ashr_i32 s31, s30, 31
	v_ashrrev_i32_e32 v31, 31, v30
	ds_read2_b32 v[32:33], v41 offset0:8 offset1:41
	ds_read2_b32 v[34:35], v41 offset0:74 offset1:107
	ds_read2_b32 v[36:37], v41 offset0:140 offset1:173
	ds_read2_b32 v[38:39], v41 offset0:206 offset1:239
	v_lshl_add_u64 v[28:29], s[30:31], 1, v[10:11]
	v_lshlrev_b64 v[30:31], 11, v[30:31]
	v_lshl_add_u64 v[30:31], v[28:29], 0, v[30:31]
	global_store_dwordx4 v[30:31], v[2:5], off
	v_or_b32_e32 v30, s6, v42
	v_cmp_lt_i32_e32 vcc, s41, v30
	v_lshlrev_b32_e32 v8, 1, v30
	v_and_b32_e32 v31, 0x6f, v30
	s_waitcnt lgkmcnt(3)
	v_cvt_pk_bf16_f32 v2, v32, v33
	s_waitcnt lgkmcnt(2)
	v_cvt_pk_bf16_f32 v3, v34, v35
	s_waitcnt lgkmcnt(1)
	v_cvt_pk_bf16_f32 v4, v36, v37
	s_waitcnt lgkmcnt(0)
	v_cvt_pk_bf16_f32 v5, v38, v39
	s_and_saveexec_b64 s[30:31], vcc
	s_xor_b64 s[30:31], exec, s[30:31]
	v_add_u32_e32 v8, 0x7fffea00, v8
	v_and_b32_e32 v8, 0x7fffff00, v8
	v_or3_b32 v30, v31, v8, s46
	s_andn2_saveexec_b64 s[30:31], s[30:31]
	v_and_or_b32 v30, v8, s48, v31
	s_or_b64 exec, exec, s[30:31]
	v_ashrrev_i32_e32 v31, 31, v30
	ds_read2_b32 v[32:33], v41 offset0:16 offset1:49
	ds_read2_b32 v[34:35], v41 offset0:82 offset1:115
	ds_read2_b32 v[36:37], v41 offset0:148 offset1:181
	ds_read2_b32 v[38:39], v41 offset0:214 offset1:247
	v_lshlrev_b64 v[30:31], 11, v[30:31]
	v_lshl_add_u64 v[30:31], v[28:29], 0, v[30:31]
	global_store_dwordx4 v[30:31], v[2:5], off
	v_or_b32_e32 v30, s6, v43
	v_cmp_lt_i32_e32 vcc, s41, v30
	v_lshlrev_b32_e32 v8, 1, v30
	v_and_b32_e32 v31, 0x77, v30
	s_waitcnt lgkmcnt(3)
	v_cvt_pk_bf16_f32 v2, v32, v33
	s_waitcnt lgkmcnt(2)
	v_cvt_pk_bf16_f32 v3, v34, v35
	s_waitcnt lgkmcnt(1)
	v_cvt_pk_bf16_f32 v4, v36, v37
	s_waitcnt lgkmcnt(0)
	v_cvt_pk_bf16_f32 v5, v38, v39
	s_and_saveexec_b64 s[30:31], vcc
	s_xor_b64 s[30:31], exec, s[30:31]
	v_add_u32_e32 v8, 0x7fffea00, v8
	v_and_b32_e32 v8, 0x7fffff00, v8
	v_or3_b32 v30, v31, v8, s46
	s_andn2_saveexec_b64 s[30:31], s[30:31]
	v_and_or_b32 v30, v8, s48, v31
	s_or_b64 exec, exec, s[30:31]
	v_ashrrev_i32_e32 v31, 31, v30
	ds_read2_b32 v[32:33], v41 offset0:24 offset1:57
	ds_read2_b32 v[34:35], v41 offset0:90 offset1:123
	ds_read2_b32 v[36:37], v41 offset0:156 offset1:189
	ds_read2_b32 v[38:39], v41 offset0:222 offset1:255
	v_lshlrev_b64 v[30:31], 11, v[30:31]
	v_lshl_add_u64 v[30:31], v[28:29], 0, v[30:31]
	global_store_dwordx4 v[30:31], v[2:5], off
	v_or_b32_e32 v30, s6, v44
	v_cmp_lt_i32_e32 vcc, s41, v30
	v_lshlrev_b32_e32 v8, 1, v30
	v_and_b32_e32 v31, 0x7f, v30
	s_waitcnt lgkmcnt(3)
	v_cvt_pk_bf16_f32 v2, v32, v33
	s_waitcnt lgkmcnt(2)
	v_cvt_pk_bf16_f32 v3, v34, v35
	s_waitcnt lgkmcnt(1)
	v_cvt_pk_bf16_f32 v4, v36, v37
	s_waitcnt lgkmcnt(0)
	v_cvt_pk_bf16_f32 v5, v38, v39
	s_and_saveexec_b64 s[6:7], vcc
	s_xor_b64 s[6:7], exec, s[6:7]
	v_add_u32_e32 v8, 0x7fffea00, v8
	v_and_b32_e32 v8, 0x7fffff00, v8
	v_or3_b32 v30, v31, v8, s46
	s_andn2_saveexec_b64 s[6:7], s[6:7]
	v_and_or_b32 v30, v8, s48, v31
	s_or_b64 exec, exec, s[6:7]
	v_ashrrev_i32_e32 v31, 31, v30
	v_lshlrev_b64 v[30:31], 11, v[30:31]
	v_lshl_add_u64 v[28:29], v[28:29], 0, v[30:31]
	global_store_dwordx4 v[28:29], v[2:5], off
	s_waitcnt lgkmcnt(0)
